# barrier trims + both k-steps of one accumulator back to back
# baseline (speedup 1.0000x reference)
.LBB0_262:
	s_add_i32 vcc_lo, s38, 2
	s_add_u32 s39, s10, 0xfff00080
	s_addc_u32 s66, s11, -1
	s_add_i32 s67, 0, 0x10000
	s_cmp_eq_u32 s35, s38
	s_cselect_b32 s87, s53, s66
	s_cselect_b32 s86, s52, s39
	s_cselect_b32 s39, s13, s49
	s_cselect_b32 s38, s15, s40
	s_add_i32 vcc_hi, 0, 0x14000
	v_add_u32_e32 v142, s67, v1
	v_add_u32_e32 v180, vcc_hi, v1
	ds_read_b128 v[130:133], v142
	ds_read_b128 v[134:137], v142 offset:1024
	ds_read_b128 v[138:141], v142 offset:2048
	ds_read_b128 v[142:145], v142 offset:3072
	ds_read_b128 v[168:171], v180
	ds_read_b128 v[172:175], v180 offset:1024
	ds_read_b128 v[176:179], v180 offset:2048
	ds_read_b128 v[180:183], v180 offset:3072
	v_lshl_add_u64 v[184:185], s[10:11], 0, v[164:165]
	s_add_i32 m0, s85, 0xc000
	ds_read_b128 v[198:201], v197
	ds_read_b128 v[202:205], v197 offset:1024
	ds_read_b128 v[206:209], v197 offset:2048
	ds_read_b128 v[210:213], v197 offset:3072
	ds_read_b128 v[214:217], v197 offset:4096
	ds_read_b128 v[218:221], v197 offset:5120
	ds_read_b128 v[222:225], v197 offset:6144
	ds_read_b128 v[226:229], v197 offset:7168
	global_load_lds_dwordx4 v[184:185], off
	v_lshl_add_u64 v[184:185], s[10:11], 0, v[166:167]
	s_add_i32 m0, s85, 0xe000
	s_nop 0
	global_load_lds_dwordx4 v[184:185], off
	s_waitcnt vmcnt(8)
	s_waitcnt lgkmcnt(0)
	s_setprio 1
	s_barrier
	v_mfma_f32_16x16x32_bf16 v[114:117], v[130:133], v[198:201], v[114:117]
	v_mfma_f32_16x16x32_bf16 v[114:117], v[134:137], v[202:205], v[114:117]
	v_mfma_f32_16x16x32_bf16 v[118:121], v[138:141], v[198:201], v[118:121]
	v_mfma_f32_16x16x32_bf16 v[118:121], v[142:145], v[202:205], v[118:121]
	v_mfma_f32_16x16x32_bf16 v[102:105], v[130:133], v[206:209], v[102:105]
	v_mfma_f32_16x16x32_bf16 v[102:105], v[134:137], v[210:213], v[102:105]
	v_mfma_f32_16x16x32_bf16 v[98:101], v[138:141], v[206:209], v[98:101]
	v_mfma_f32_16x16x32_bf16 v[98:101], v[142:145], v[210:213], v[98:101]
	v_mfma_f32_16x16x32_bf16 v[86:89], v[130:133], v[214:217], v[86:89]
	v_mfma_f32_16x16x32_bf16 v[86:89], v[134:137], v[218:221], v[86:89]
	v_mfma_f32_16x16x32_bf16 v[82:85], v[138:141], v[214:217], v[82:85]
	v_mfma_f32_16x16x32_bf16 v[82:85], v[142:145], v[218:221], v[82:85]
	v_mfma_f32_16x16x32_bf16 v[54:57], v[130:133], v[222:225], v[54:57]
	v_mfma_f32_16x16x32_bf16 v[54:57], v[134:137], v[226:229], v[54:57]
	v_mfma_f32_16x16x32_bf16 v[50:53], v[138:141], v[222:225], v[50:53]
	v_mfma_f32_16x16x32_bf16 v[50:53], v[142:145], v[226:229], v[50:53]
	s_setprio 0
	s_setprio 1
	v_mfma_f32_16x16x32_bf16 v[126:129], v[168:171], v[198:201], v[126:129]
	v_mfma_f32_16x16x32_bf16 v[126:129], v[172:175], v[202:205], v[126:129]
	v_mfma_f32_16x16x32_bf16 v[122:125], v[176:179], v[198:201], v[122:125]
	v_mfma_f32_16x16x32_bf16 v[122:125], v[180:183], v[202:205], v[122:125]
	v_mfma_f32_16x16x32_bf16 v[110:113], v[168:171], v[206:209], v[110:113]
	v_mfma_f32_16x16x32_bf16 v[110:113], v[172:175], v[210:213], v[110:113]
	v_mfma_f32_16x16x32_bf16 v[106:109], v[176:179], v[206:209], v[106:109]
	v_mfma_f32_16x16x32_bf16 v[106:109], v[180:183], v[210:213], v[106:109]
	v_mfma_f32_16x16x32_bf16 v[94:97], v[168:171], v[214:217], v[94:97]
	v_mfma_f32_16x16x32_bf16 v[94:97], v[172:175], v[218:221], v[94:97]
	v_mfma_f32_16x16x32_bf16 v[90:93], v[176:179], v[214:217], v[90:93]
	v_mfma_f32_16x16x32_bf16 v[90:93], v[180:183], v[218:221], v[90:93]
	v_mfma_f32_16x16x32_bf16 v[70:73], v[168:171], v[222:225], v[70:73]
	v_mfma_f32_16x16x32_bf16 v[70:73], v[172:175], v[226:229], v[70:73]
	v_mfma_f32_16x16x32_bf16 v[66:69], v[176:179], v[222:225], v[66:69]
	v_mfma_f32_16x16x32_bf16 v[66:69], v[180:183], v[226:229], v[66:69]
	s_barrier
	s_setprio 0
	s_add_i32 s66, s67, s97
	v_lshl_add_u64 v[184:185], s[38:39], 0, v[156:157]
	s_mov_b32 m0, s66
	ds_read_b128 v[198:201], v197 offset:16384
	ds_read_b128 v[202:205], v197 offset:17408
	ds_read_b128 v[206:209], v197 offset:18432
	ds_read_b128 v[210:213], v197 offset:19456
	ds_read_b128 v[214:217], v197 offset:20480
	ds_read_b128 v[218:221], v197 offset:21504
	ds_read_b128 v[222:225], v197 offset:22528
	ds_read_b128 v[226:229], v197 offset:23552
	global_load_lds_dwordx4 v[184:185], off
	s_add_i32 m0, s66, 0x2000
	s_add_u32 s66, s38, 0x100000
	v_lshl_add_u64 v[230:231], s[38:39], 0, v[160:161]
	s_addc_u32 s67, s39, 0
	s_add_i32 vcc_hi, vcc_hi, s97
	global_load_lds_dwordx4 v[230:231], off
	v_lshl_add_u64 v[232:233], s[66:67], 0, v[156:157]
	s_mov_b32 m0, vcc_hi
	v_lshl_add_u64 v[234:235], s[86:87], 0, v[158:159]
	global_load_lds_dwordx4 v[232:233], off
	v_lshl_add_u64 v[232:233], s[66:67], 0, v[160:161]
	s_add_i32 m0, vcc_hi, 0x2000
	s_nop 0
	global_load_lds_dwordx4 v[232:233], off
	v_lshl_add_u64 v[232:233], s[86:87], 0, v[154:155]
	s_mov_b32 m0, s85
	s_nop 0
	global_load_lds_dwordx4 v[232:233], off
	s_mov_b32 m0, s92
	s_nop 0
	global_load_lds_dwordx4 v[234:235], off
	s_waitcnt vmcnt(8)
	s_waitcnt lgkmcnt(0)
	s_setprio 1
	s_barrier
	v_mfma_f32_16x16x32_bf16 v[62:65], v[130:133], v[198:201], v[62:65]
	v_mfma_f32_16x16x32_bf16 v[62:65], v[134:137], v[202:205], v[62:65]
	v_mfma_f32_16x16x32_bf16 v[58:61], v[138:141], v[198:201], v[58:61]
	v_mfma_f32_16x16x32_bf16 v[58:61], v[142:145], v[202:205], v[58:61]
	v_mfma_f32_16x16x32_bf16 v[38:41], v[130:133], v[206:209], v[38:41]
	v_mfma_f32_16x16x32_bf16 v[38:41], v[134:137], v[210:213], v[38:41]
	v_mfma_f32_16x16x32_bf16 v[34:37], v[138:141], v[206:209], v[34:37]
	v_mfma_f32_16x16x32_bf16 v[34:37], v[142:145], v[210:213], v[34:37]
	v_mfma_f32_16x16x32_bf16 v[22:25], v[130:133], v[214:217], v[22:25]
	v_mfma_f32_16x16x32_bf16 v[22:25], v[134:137], v[218:221], v[22:25]
	v_mfma_f32_16x16x32_bf16 v[18:21], v[138:141], v[214:217], v[18:21]
	v_mfma_f32_16x16x32_bf16 v[18:21], v[142:145], v[218:221], v[18:21]
	v_mfma_f32_16x16x32_bf16 v[6:9], v[130:133], v[222:225], v[6:9]
	v_mfma_f32_16x16x32_bf16 v[6:9], v[134:137], v[226:229], v[6:9]
	v_mfma_f32_16x16x32_bf16 v[2:5], v[138:141], v[222:225], v[2:5]
	v_mfma_f32_16x16x32_bf16 v[2:5], v[142:145], v[226:229], v[2:5]
	s_setprio 0
	s_setprio 1
	v_mfma_f32_16x16x32_bf16 v[78:81], v[168:171], v[198:201], v[78:81]
	v_mfma_f32_16x16x32_bf16 v[78:81], v[172:175], v[202:205], v[78:81]
	v_mfma_f32_16x16x32_bf16 v[74:77], v[176:179], v[198:201], v[74:77]
	v_mfma_f32_16x16x32_bf16 v[74:77], v[180:183], v[202:205], v[74:77]
	v_mfma_f32_16x16x32_bf16 v[46:49], v[168:171], v[206:209], v[46:49]
	v_mfma_f32_16x16x32_bf16 v[46:49], v[172:175], v[210:213], v[46:49]
	v_mfma_f32_16x16x32_bf16 v[42:45], v[176:179], v[206:209], v[42:45]
	v_mfma_f32_16x16x32_bf16 v[42:45], v[180:183], v[210:213], v[42:45]
	v_mfma_f32_16x16x32_bf16 v[30:33], v[168:171], v[214:217], v[30:33]
	v_mfma_f32_16x16x32_bf16 v[30:33], v[172:175], v[218:221], v[30:33]
	v_mfma_f32_16x16x32_bf16 v[26:29], v[176:179], v[214:217], v[26:29]
	v_mfma_f32_16x16x32_bf16 v[26:29], v[180:183], v[218:221], v[26:29]
	v_mfma_f32_16x16x32_bf16 v[14:17], v[168:171], v[222:225], v[14:17]
	v_mfma_f32_16x16x32_bf16 v[14:17], v[172:175], v[226:229], v[14:17]
	v_mfma_f32_16x16x32_bf16 v[10:13], v[176:179], v[222:225], v[10:13]
	v_mfma_f32_16x16x32_bf16 v[10:13], v[180:183], v[226:229], v[10:13]
	s_barrier
	s_setprio 0
	s_add_i32 vcc_hi, 0, 0x18000
	s_add_i32 s56, 0, 0x1c000
	v_add_u32_e32 v142, vcc_hi, v1
	v_add_u32_e32 v180, s56, v1
	ds_read_b128 v[130:133], v142
	ds_read_b128 v[134:137], v142 offset:1024
	ds_read_b128 v[138:141], v142 offset:2048
	ds_read_b128 v[142:145], v142 offset:3072
	ds_read_b128 v[168:171], v180
	ds_read_b128 v[172:175], v180 offset:1024
	ds_read_b128 v[176:179], v180 offset:2048
	ds_read_b128 v[180:183], v180 offset:3072
	s_add_u32 s66, s86, 0x100000
	s_addc_u32 s67, s87, 0
	s_mov_b32 m0, s93
	v_lshl_add_u64 v[236:237], s[66:67], 0, v[154:155]
	ds_read_b128 v[198:201], v197 offset:32768
	ds_read_b128 v[202:205], v197 offset:33792
	ds_read_b128 v[206:209], v197 offset:34816
	ds_read_b128 v[210:213], v197 offset:35840
	ds_read_b128 v[214:217], v197 offset:36864
	ds_read_b128 v[218:221], v197 offset:37888
	ds_read_b128 v[222:225], v197 offset:38912
	ds_read_b128 v[226:229], v197 offset:39936
	global_load_lds_dwordx4 v[236:237], off
	v_lshl_add_u64 v[236:237], s[66:67], 0, v[158:159]
	s_mov_b32 m0, s42
	s_nop 0
	global_load_lds_dwordx4 v[236:237], off
	s_waitcnt vmcnt(8)
	s_waitcnt lgkmcnt(0)
	s_setprio 1
	s_barrier
	v_mfma_f32_16x16x32_bf16 v[114:117], v[130:133], v[198:201], v[114:117]
	v_mfma_f32_16x16x32_bf16 v[114:117], v[134:137], v[202:205], v[114:117]
	v_mfma_f32_16x16x32_bf16 v[118:121], v[138:141], v[198:201], v[118:121]
	v_mfma_f32_16x16x32_bf16 v[118:121], v[142:145], v[202:205], v[118:121]
	v_mfma_f32_16x16x32_bf16 v[102:105], v[130:133], v[206:209], v[102:105]
	v_mfma_f32_16x16x32_bf16 v[102:105], v[134:137], v[210:213], v[102:105]
	v_mfma_f32_16x16x32_bf16 v[98:101], v[138:141], v[206:209], v[98:101]
	v_mfma_f32_16x16x32_bf16 v[98:101], v[142:145], v[210:213], v[98:101]
	v_mfma_f32_16x16x32_bf16 v[86:89], v[130:133], v[214:217], v[86:89]
	v_mfma_f32_16x16x32_bf16 v[86:89], v[134:137], v[218:221], v[86:89]
	v_mfma_f32_16x16x32_bf16 v[82:85], v[138:141], v[214:217], v[82:85]
	v_mfma_f32_16x16x32_bf16 v[82:85], v[142:145], v[218:221], v[82:85]
	v_mfma_f32_16x16x32_bf16 v[54:57], v[130:133], v[222:225], v[54:57]
	v_mfma_f32_16x16x32_bf16 v[54:57], v[134:137], v[226:229], v[54:57]
	v_mfma_f32_16x16x32_bf16 v[50:53], v[138:141], v[222:225], v[50:53]
	v_mfma_f32_16x16x32_bf16 v[50:53], v[142:145], v[226:229], v[50:53]
	s_setprio 0
	s_setprio 1
	v_mfma_f32_16x16x32_bf16 v[126:129], v[168:171], v[198:201], v[126:129]
	v_mfma_f32_16x16x32_bf16 v[126:129], v[172:175], v[202:205], v[126:129]
	v_mfma_f32_16x16x32_bf16 v[122:125], v[176:179], v[198:201], v[122:125]
	v_mfma_f32_16x16x32_bf16 v[122:125], v[180:183], v[202:205], v[122:125]
	v_mfma_f32_16x16x32_bf16 v[110:113], v[168:171], v[206:209], v[110:113]
	v_mfma_f32_16x16x32_bf16 v[110:113], v[172:175], v[210:213], v[110:113]
	v_mfma_f32_16x16x32_bf16 v[106:109], v[176:179], v[206:209], v[106:109]
	v_mfma_f32_16x16x32_bf16 v[106:109], v[180:183], v[210:213], v[106:109]
	v_mfma_f32_16x16x32_bf16 v[94:97], v[168:171], v[214:217], v[94:97]
	v_mfma_f32_16x16x32_bf16 v[94:97], v[172:175], v[218:221], v[94:97]
	v_mfma_f32_16x16x32_bf16 v[90:93], v[176:179], v[214:217], v[90:93]
	v_mfma_f32_16x16x32_bf16 v[90:93], v[180:183], v[218:221], v[90:93]
	v_mfma_f32_16x16x32_bf16 v[70:73], v[168:171], v[222:225], v[70:73]
	v_mfma_f32_16x16x32_bf16 v[70:73], v[172:175], v[226:229], v[70:73]
	v_mfma_f32_16x16x32_bf16 v[66:69], v[176:179], v[222:225], v[66:69]
	v_mfma_f32_16x16x32_bf16 v[66:69], v[180:183], v[226:229], v[66:69]
	s_barrier
	s_setprio 0
	s_add_i32 s57, vcc_hi, s97
	v_lshl_add_u64 v[184:185], v[184:185], 0, s[94:95]
	s_mov_b32 m0, s57
	ds_read_b128 v[198:201], v197 offset:49152
	ds_read_b128 v[202:205], v197 offset:50176
	ds_read_b128 v[206:209], v197 offset:51200
	ds_read_b128 v[210:213], v197 offset:52224
	ds_read_b128 v[214:217], v197 offset:53248
	ds_read_b128 v[218:221], v197 offset:54272
	ds_read_b128 v[222:225], v197 offset:55296
	ds_read_b128 v[226:229], v197 offset:56320
	global_load_lds_dwordx4 v[184:185], off
	s_add_i32 m0, s57, 0x2000
	s_add_u32 s38, s38, 0x100080
	v_lshl_add_u64 v[184:185], v[230:231], 0, s[94:95]
	s_addc_u32 s39, s39, 0
	s_add_i32 s56, s56, s97
	global_load_lds_dwordx4 v[184:185], off
	v_lshl_add_u64 v[184:185], s[38:39], 0, v[156:157]
	s_mov_b32 m0, s56
	s_nop 0
	global_load_lds_dwordx4 v[184:185], off
	v_lshl_add_u64 v[184:185], s[38:39], 0, v[160:161]
	s_add_i32 m0, s56, 0x2000
	s_nop 0
	global_load_lds_dwordx4 v[184:185], off
	v_lshl_add_u64 v[184:185], v[232:233], 0, s[94:95]
	s_mov_b32 m0, s43
	s_nop 0
	global_load_lds_dwordx4 v[184:185], off
	v_lshl_add_u64 v[184:185], v[234:235], 0, s[94:95]
	s_mov_b32 m0, s90
	s_nop 0
	global_load_lds_dwordx4 v[184:185], off
	s_waitcnt vmcnt(8)
	s_waitcnt lgkmcnt(0)
	s_setprio 1
	s_barrier
	v_mfma_f32_16x16x32_bf16 v[62:65], v[130:133], v[198:201], v[62:65]
	v_mfma_f32_16x16x32_bf16 v[62:65], v[134:137], v[202:205], v[62:65]
	v_mfma_f32_16x16x32_bf16 v[58:61], v[138:141], v[198:201], v[58:61]
	v_mfma_f32_16x16x32_bf16 v[58:61], v[142:145], v[202:205], v[58:61]
	v_mfma_f32_16x16x32_bf16 v[38:41], v[130:133], v[206:209], v[38:41]
	v_mfma_f32_16x16x32_bf16 v[38:41], v[134:137], v[210:213], v[38:41]
	v_mfma_f32_16x16x32_bf16 v[34:37], v[138:141], v[206:209], v[34:37]
	v_mfma_f32_16x16x32_bf16 v[34:37], v[142:145], v[210:213], v[34:37]
	v_mfma_f32_16x16x32_bf16 v[22:25], v[130:133], v[214:217], v[22:25]
	v_mfma_f32_16x16x32_bf16 v[22:25], v[134:137], v[218:221], v[22:25]
	v_mfma_f32_16x16x32_bf16 v[18:21], v[138:141], v[214:217], v[18:21]
	v_mfma_f32_16x16x32_bf16 v[18:21], v[142:145], v[218:221], v[18:21]
	v_mfma_f32_16x16x32_bf16 v[6:9], v[130:133], v[222:225], v[6:9]
	v_mfma_f32_16x16x32_bf16 v[6:9], v[134:137], v[226:229], v[6:9]
	v_mfma_f32_16x16x32_bf16 v[2:5], v[138:141], v[222:225], v[2:5]
	v_mfma_f32_16x16x32_bf16 v[2:5], v[142:145], v[226:229], v[2:5]
	s_setprio 0
	s_setprio 1
	v_mfma_f32_16x16x32_bf16 v[78:81], v[168:171], v[198:201], v[78:81]
	v_mfma_f32_16x16x32_bf16 v[78:81], v[172:175], v[202:205], v[78:81]
	v_mfma_f32_16x16x32_bf16 v[74:77], v[176:179], v[198:201], v[74:77]
	v_mfma_f32_16x16x32_bf16 v[74:77], v[180:183], v[202:205], v[74:77]
	v_mfma_f32_16x16x32_bf16 v[46:49], v[168:171], v[206:209], v[46:49]
	v_mfma_f32_16x16x32_bf16 v[46:49], v[172:175], v[210:213], v[46:49]
	v_mfma_f32_16x16x32_bf16 v[42:45], v[176:179], v[206:209], v[42:45]
	v_mfma_f32_16x16x32_bf16 v[42:45], v[180:183], v[210:213], v[42:45]
	v_mfma_f32_16x16x32_bf16 v[30:33], v[168:171], v[214:217], v[30:33]
	v_mfma_f32_16x16x32_bf16 v[30:33], v[172:175], v[218:221], v[30:33]
	v_mfma_f32_16x16x32_bf16 v[26:29], v[176:179], v[214:217], v[26:29]
	v_mfma_f32_16x16x32_bf16 v[26:29], v[180:183], v[218:221], v[26:29]
	v_mfma_f32_16x16x32_bf16 v[14:17], v[168:171], v[222:225], v[14:17]
	v_mfma_f32_16x16x32_bf16 v[14:17], v[172:175], v[226:229], v[14:17]
	v_mfma_f32_16x16x32_bf16 v[10:13], v[176:179], v[222:225], v[10:13]
	v_mfma_f32_16x16x32_bf16 v[10:13], v[180:183], v[226:229], v[10:13]
	s_barrier
	s_setprio 0
	s_add_u32 s40, s40, 0x100
	s_addc_u32 s49, s49, 0
	s_add_u32 s10, s10, 0x100
	s_addc_u32 s11, s11, 0
	s_cmp_ge_u32 vcc_lo, s19
	s_mov_b32 s38, vcc_lo
	s_cbranch_scc0 .LBB0_262
	v_readlane_b32 s10, v254, 27
	v_readlane_b32 s11, v254, 28
	s_and_b64 vcc, exec, s[10:11]
	s_cbranch_vccz .LBB0_270
	s_barrier
	s_cmp_lt_i32 s18, 0
	s_mov_b64 s[10:11], -1
	s_cbranch_scc1 .LBB0_271

.LBB0_1693:
	ds_read_b128 v[128:131], v169
	ds_read_b128 v[132:135], v169 offset:1024
	ds_read_b128 v[136:139], v169 offset:2048
	ds_read_b128 v[140:143], v169 offset:3072
	ds_read_b128 v[158:161], v170
	ds_read_b128 v[162:165], v170 offset:1024
	ds_read_b128 v[172:175], v170 offset:2048
	ds_read_b128 v[176:179], v170 offset:3072
	s_add_u32 s24, s22, 0xfff80080
	s_addc_u32 s25, s23, -1
	s_cmp_eq_u32 s36, 4
	s_cselect_b32 s27, s5, s25
	s_cselect_b32 s26, s4, s24
	s_cselect_b32 s25, s13, s35
	s_cselect_b32 s24, s15, s34
	v_lshl_add_u64 v[212:213], s[22:23], 0, v[152:153]
	s_add_i32 m0, s94, 0xc000
	ds_read_b128 v[180:183], v171
	ds_read_b128 v[184:187], v171 offset:1024
	ds_read_b128 v[188:191], v171 offset:2048
	ds_read_b128 v[192:195], v171 offset:3072
	ds_read_b128 v[196:199], v171 offset:4096
	ds_read_b128 v[200:203], v171 offset:5120
	ds_read_b128 v[204:207], v171 offset:6144
	ds_read_b128 v[208:211], v171 offset:7168
	global_load_lds_dwordx4 v[212:213], off
	v_lshl_add_u64 v[212:213], s[22:23], 0, v[154:155]
	s_add_i32 m0, s94, 0xe000
	s_nop 0
	global_load_lds_dwordx4 v[212:213], off
	s_waitcnt vmcnt(8)
	s_waitcnt lgkmcnt(0)
	s_setprio 1
	s_barrier
	v_mfma_f32_16x16x32_bf16 v[80:83], v[128:131], v[180:183], v[80:83]
	v_mfma_f32_16x16x32_bf16 v[80:83], v[132:135], v[184:187], v[80:83]
	v_mfma_f32_16x16x32_bf16 v[92:95], v[136:139], v[180:183], v[92:95]
	v_mfma_f32_16x16x32_bf16 v[92:95], v[140:143], v[184:187], v[92:95]
	v_mfma_f32_16x16x32_bf16 v[84:87], v[128:131], v[188:191], v[84:87]
	v_mfma_f32_16x16x32_bf16 v[84:87], v[132:135], v[192:195], v[84:87]
	v_mfma_f32_16x16x32_bf16 v[96:99], v[136:139], v[188:191], v[96:99]
	v_mfma_f32_16x16x32_bf16 v[96:99], v[140:143], v[192:195], v[96:99]
	v_mfma_f32_16x16x32_bf16 v[88:91], v[128:131], v[196:199], v[88:91]
	v_mfma_f32_16x16x32_bf16 v[88:91], v[132:135], v[200:203], v[88:91]
	v_mfma_f32_16x16x32_bf16 v[100:103], v[136:139], v[196:199], v[100:103]
	v_mfma_f32_16x16x32_bf16 v[100:103], v[140:143], v[200:203], v[100:103]
	v_mfma_f32_16x16x32_bf16 v[72:75], v[128:131], v[204:207], v[72:75]
	v_mfma_f32_16x16x32_bf16 v[72:75], v[132:135], v[208:211], v[72:75]
	v_mfma_f32_16x16x32_bf16 v[76:79], v[136:139], v[204:207], v[76:79]
	v_mfma_f32_16x16x32_bf16 v[76:79], v[140:143], v[208:211], v[76:79]
	s_setprio 0
	s_setprio 1
	v_mfma_f32_16x16x32_bf16 v[104:107], v[158:161], v[180:183], v[104:107]
	v_mfma_f32_16x16x32_bf16 v[104:107], v[162:165], v[184:187], v[104:107]
	v_mfma_f32_16x16x32_bf16 v[116:119], v[172:175], v[180:183], v[116:119]
	v_mfma_f32_16x16x32_bf16 v[116:119], v[176:179], v[184:187], v[116:119]
	v_mfma_f32_16x16x32_bf16 v[108:111], v[158:161], v[188:191], v[108:111]
	v_mfma_f32_16x16x32_bf16 v[108:111], v[162:165], v[192:195], v[108:111]
	v_mfma_f32_16x16x32_bf16 v[120:123], v[172:175], v[188:191], v[120:123]
	v_mfma_f32_16x16x32_bf16 v[120:123], v[176:179], v[192:195], v[120:123]
	v_mfma_f32_16x16x32_bf16 v[112:115], v[158:161], v[196:199], v[112:115]
	v_mfma_f32_16x16x32_bf16 v[112:115], v[162:165], v[200:203], v[112:115]
	v_mfma_f32_16x16x32_bf16 v[124:127], v[172:175], v[196:199], v[124:127]
	v_mfma_f32_16x16x32_bf16 v[124:127], v[176:179], v[200:203], v[124:127]
	v_mfma_f32_16x16x32_bf16 v[68:71], v[158:161], v[204:207], v[68:71]
	v_mfma_f32_16x16x32_bf16 v[68:71], v[162:165], v[208:211], v[68:71]
	v_mfma_f32_16x16x32_bf16 v[64:67], v[172:175], v[204:207], v[64:67]
	v_mfma_f32_16x16x32_bf16 v[64:67], v[176:179], v[208:211], v[64:67]
	s_barrier
	s_setprio 0
	s_add_i32 s37, s31, s97
	v_lshl_add_u64 v[212:213], s[24:25], 0, v[148:149]
	s_mov_b32 m0, s37
	ds_read_b128 v[180:183], v171 offset:16384
	ds_read_b128 v[184:187], v171 offset:17408
	ds_read_b128 v[188:191], v171 offset:18432
	ds_read_b128 v[192:195], v171 offset:19456
	ds_read_b128 v[196:199], v171 offset:20480
	ds_read_b128 v[200:203], v171 offset:21504
	ds_read_b128 v[204:207], v171 offset:22528
	ds_read_b128 v[208:211], v171 offset:23552
	global_load_lds_dwordx4 v[212:213], off
	s_add_i32 m0, s37, 0x2000
	s_add_u32 s38, s24, 0x20000
	v_lshl_add_u64 v[214:215], s[24:25], 0, v[144:145]
	s_addc_u32 s39, s25, 0
	s_add_i32 s37, s33, s97
	global_load_lds_dwordx4 v[214:215], off
	v_lshl_add_u64 v[216:217], s[38:39], 0, v[148:149]
	s_mov_b32 m0, s37
	v_lshl_add_u64 v[218:219], s[26:27], 0, v[146:147]
	global_load_lds_dwordx4 v[216:217], off
	v_lshl_add_u64 v[216:217], s[38:39], 0, v[144:145]
	s_add_i32 m0, s37, 0x2000
	s_nop 0
	global_load_lds_dwordx4 v[216:217], off
	v_lshl_add_u64 v[216:217], s[26:27], 0, v[150:151]
	s_mov_b32 m0, s94
	s_nop 0
	global_load_lds_dwordx4 v[216:217], off
	s_mov_b32 m0, s3
	s_nop 0
	global_load_lds_dwordx4 v[218:219], off
	s_waitcnt vmcnt(8)
	s_waitcnt lgkmcnt(0)
	s_setprio 1
	s_barrier
	v_mfma_f32_16x16x32_bf16 v[48:51], v[128:131], v[180:183], v[48:51]
	v_mfma_f32_16x16x32_bf16 v[48:51], v[132:135], v[184:187], v[48:51]
	v_mfma_f32_16x16x32_bf16 v[52:55], v[136:139], v[180:183], v[52:55]
	v_mfma_f32_16x16x32_bf16 v[52:55], v[140:143], v[184:187], v[52:55]
	v_mfma_f32_16x16x32_bf16 v[32:35], v[128:131], v[188:191], v[32:35]
	v_mfma_f32_16x16x32_bf16 v[32:35], v[132:135], v[192:195], v[32:35]
	v_mfma_f32_16x16x32_bf16 v[36:39], v[136:139], v[188:191], v[36:39]
	v_mfma_f32_16x16x32_bf16 v[36:39], v[140:143], v[192:195], v[36:39]
	v_mfma_f32_16x16x32_bf16 v[16:19], v[128:131], v[196:199], v[16:19]
	v_mfma_f32_16x16x32_bf16 v[16:19], v[132:135], v[200:203], v[16:19]
	v_mfma_f32_16x16x32_bf16 v[20:23], v[136:139], v[196:199], v[20:23]
	v_mfma_f32_16x16x32_bf16 v[20:23], v[140:143], v[200:203], v[20:23]
	v_mfma_f32_16x16x32_bf16 v[0:3], v[128:131], v[204:207], v[0:3]
	v_mfma_f32_16x16x32_bf16 v[0:3], v[132:135], v[208:211], v[0:3]
	v_mfma_f32_16x16x32_bf16 v[4:7], v[136:139], v[204:207], v[4:7]
	v_mfma_f32_16x16x32_bf16 v[4:7], v[140:143], v[208:211], v[4:7]
	s_setprio 0
	s_setprio 1
	v_mfma_f32_16x16x32_bf16 v[56:59], v[158:161], v[180:183], v[56:59]
	v_mfma_f32_16x16x32_bf16 v[56:59], v[162:165], v[184:187], v[56:59]
	v_mfma_f32_16x16x32_bf16 v[60:63], v[172:175], v[180:183], v[60:63]
	v_mfma_f32_16x16x32_bf16 v[60:63], v[176:179], v[184:187], v[60:63]
	v_mfma_f32_16x16x32_bf16 v[40:43], v[158:161], v[188:191], v[40:43]
	v_mfma_f32_16x16x32_bf16 v[40:43], v[162:165], v[192:195], v[40:43]
	v_mfma_f32_16x16x32_bf16 v[44:47], v[172:175], v[188:191], v[44:47]
	v_mfma_f32_16x16x32_bf16 v[44:47], v[176:179], v[192:195], v[44:47]
	v_mfma_f32_16x16x32_bf16 v[24:27], v[158:161], v[196:199], v[24:27]
	v_mfma_f32_16x16x32_bf16 v[24:27], v[162:165], v[200:203], v[24:27]
	v_mfma_f32_16x16x32_bf16 v[28:31], v[172:175], v[196:199], v[28:31]
	v_mfma_f32_16x16x32_bf16 v[28:31], v[176:179], v[200:203], v[28:31]
	v_mfma_f32_16x16x32_bf16 v[8:11], v[158:161], v[204:207], v[8:11]
	v_mfma_f32_16x16x32_bf16 v[8:11], v[162:165], v[208:211], v[8:11]
	v_mfma_f32_16x16x32_bf16 v[12:15], v[172:175], v[204:207], v[12:15]
	v_mfma_f32_16x16x32_bf16 v[12:15], v[176:179], v[208:211], v[12:15]
	s_barrier
	s_setprio 0
	s_add_i32 s37, 0, 0x18000
	s_add_i32 s38, 0, 0x1c000
	v_add_u32_e32 v140, s37, v167
	v_add_u32_e32 v176, s38, v167
	ds_read_b128 v[128:131], v140
	ds_read_b128 v[132:135], v140 offset:1024
	ds_read_b128 v[136:139], v140 offset:2048
	ds_read_b128 v[140:143], v140 offset:3072
	ds_read_b128 v[158:161], v176
	ds_read_b128 v[162:165], v176 offset:1024
	ds_read_b128 v[172:175], v176 offset:2048
	ds_read_b128 v[176:179], v176 offset:3072
	s_add_u32 s26, s26, 0x80000
	s_addc_u32 s27, s27, 0
	s_mov_b32 m0, s7
	v_lshl_add_u64 v[220:221], s[26:27], 0, v[150:151]
	ds_read_b128 v[180:183], v171 offset:32768
	ds_read_b128 v[184:187], v171 offset:33792
	ds_read_b128 v[188:191], v171 offset:34816
	ds_read_b128 v[192:195], v171 offset:35840
	ds_read_b128 v[196:199], v171 offset:36864
	ds_read_b128 v[200:203], v171 offset:37888
	ds_read_b128 v[204:207], v171 offset:38912
	ds_read_b128 v[208:211], v171 offset:39936
	global_load_lds_dwordx4 v[220:221], off
	v_lshl_add_u64 v[220:221], s[26:27], 0, v[146:147]
	s_mov_b32 m0, s19
	s_nop 0
	global_load_lds_dwordx4 v[220:221], off
	s_waitcnt vmcnt(8)
	s_waitcnt lgkmcnt(0)
	s_setprio 1
	s_barrier
	v_mfma_f32_16x16x32_bf16 v[80:83], v[128:131], v[180:183], v[80:83]
	v_mfma_f32_16x16x32_bf16 v[80:83], v[132:135], v[184:187], v[80:83]
	v_mfma_f32_16x16x32_bf16 v[92:95], v[136:139], v[180:183], v[92:95]
	v_mfma_f32_16x16x32_bf16 v[92:95], v[140:143], v[184:187], v[92:95]
	v_mfma_f32_16x16x32_bf16 v[84:87], v[128:131], v[188:191], v[84:87]
	v_mfma_f32_16x16x32_bf16 v[84:87], v[132:135], v[192:195], v[84:87]
	v_mfma_f32_16x16x32_bf16 v[96:99], v[136:139], v[188:191], v[96:99]
	v_mfma_f32_16x16x32_bf16 v[96:99], v[140:143], v[192:195], v[96:99]
	v_mfma_f32_16x16x32_bf16 v[88:91], v[128:131], v[196:199], v[88:91]
	v_mfma_f32_16x16x32_bf16 v[88:91], v[132:135], v[200:203], v[88:91]
	v_mfma_f32_16x16x32_bf16 v[100:103], v[136:139], v[196:199], v[100:103]
	v_mfma_f32_16x16x32_bf16 v[100:103], v[140:143], v[200:203], v[100:103]
	v_mfma_f32_16x16x32_bf16 v[72:75], v[128:131], v[204:207], v[72:75]
	v_mfma_f32_16x16x32_bf16 v[72:75], v[132:135], v[208:211], v[72:75]
	v_mfma_f32_16x16x32_bf16 v[76:79], v[136:139], v[204:207], v[76:79]
	v_mfma_f32_16x16x32_bf16 v[76:79], v[140:143], v[208:211], v[76:79]
	s_setprio 0
	s_setprio 1
	v_mfma_f32_16x16x32_bf16 v[104:107], v[158:161], v[180:183], v[104:107]
	v_mfma_f32_16x16x32_bf16 v[104:107], v[162:165], v[184:187], v[104:107]
	v_mfma_f32_16x16x32_bf16 v[116:119], v[172:175], v[180:183], v[116:119]
	v_mfma_f32_16x16x32_bf16 v[116:119], v[176:179], v[184:187], v[116:119]
	v_mfma_f32_16x16x32_bf16 v[108:111], v[158:161], v[188:191], v[108:111]
	v_mfma_f32_16x16x32_bf16 v[108:111], v[162:165], v[192:195], v[108:111]
	v_mfma_f32_16x16x32_bf16 v[120:123], v[172:175], v[188:191], v[120:123]
	v_mfma_f32_16x16x32_bf16 v[120:123], v[176:179], v[192:195], v[120:123]
	v_mfma_f32_16x16x32_bf16 v[112:115], v[158:161], v[196:199], v[112:115]
	v_mfma_f32_16x16x32_bf16 v[112:115], v[162:165], v[200:203], v[112:115]
	v_mfma_f32_16x16x32_bf16 v[124:127], v[172:175], v[196:199], v[124:127]
	v_mfma_f32_16x16x32_bf16 v[124:127], v[176:179], v[200:203], v[124:127]
	v_mfma_f32_16x16x32_bf16 v[68:71], v[158:161], v[204:207], v[68:71]
	v_mfma_f32_16x16x32_bf16 v[68:71], v[162:165], v[208:211], v[68:71]
	v_mfma_f32_16x16x32_bf16 v[64:67], v[172:175], v[204:207], v[64:67]
	v_mfma_f32_16x16x32_bf16 v[64:67], v[176:179], v[208:211], v[64:67]
	s_barrier
	s_setprio 0
	s_add_i32 s26, s37, s97
	v_lshl_add_u64 v[212:213], v[212:213], 0, s[0:1]
	s_mov_b32 m0, s26
	ds_read_b128 v[180:183], v171 offset:49152
	ds_read_b128 v[184:187], v171 offset:50176
	ds_read_b128 v[188:191], v171 offset:51200
	ds_read_b128 v[192:195], v171 offset:52224
	ds_read_b128 v[196:199], v171 offset:53248
	ds_read_b128 v[200:203], v171 offset:54272
	ds_read_b128 v[204:207], v171 offset:55296
	ds_read_b128 v[208:211], v171 offset:56320
	global_load_lds_dwordx4 v[212:213], off
	s_add_i32 m0, s26, 0x2000
	s_add_u32 s24, s24, 0x20080
	v_lshl_add_u64 v[212:213], v[214:215], 0, s[0:1]
	s_addc_u32 s25, s25, 0
	s_add_i32 s26, s38, s97
	global_load_lds_dwordx4 v[212:213], off
	v_lshl_add_u64 v[212:213], s[24:25], 0, v[148:149]
	s_mov_b32 m0, s26
	s_nop 0
	global_load_lds_dwordx4 v[212:213], off
	v_lshl_add_u64 v[212:213], s[24:25], 0, v[144:145]
	s_add_i32 m0, s26, 0x2000
	s_nop 0
	global_load_lds_dwordx4 v[212:213], off
	v_lshl_add_u64 v[212:213], v[216:217], 0, s[0:1]
	s_mov_b32 m0, s28
	s_nop 0
	global_load_lds_dwordx4 v[212:213], off
	v_lshl_add_u64 v[212:213], v[218:219], 0, s[0:1]
	s_mov_b32 m0, s29
	s_nop 0
	global_load_lds_dwordx4 v[212:213], off
	s_waitcnt vmcnt(8)
	s_waitcnt lgkmcnt(0)
	s_setprio 1
	s_barrier
	v_mfma_f32_16x16x32_bf16 v[48:51], v[128:131], v[180:183], v[48:51]
	v_mfma_f32_16x16x32_bf16 v[48:51], v[132:135], v[184:187], v[48:51]
	v_mfma_f32_16x16x32_bf16 v[52:55], v[136:139], v[180:183], v[52:55]
	v_mfma_f32_16x16x32_bf16 v[52:55], v[140:143], v[184:187], v[52:55]
	v_mfma_f32_16x16x32_bf16 v[32:35], v[128:131], v[188:191], v[32:35]
	v_mfma_f32_16x16x32_bf16 v[32:35], v[132:135], v[192:195], v[32:35]
	v_mfma_f32_16x16x32_bf16 v[36:39], v[136:139], v[188:191], v[36:39]
	v_mfma_f32_16x16x32_bf16 v[36:39], v[140:143], v[192:195], v[36:39]
	v_mfma_f32_16x16x32_bf16 v[16:19], v[128:131], v[196:199], v[16:19]
	v_mfma_f32_16x16x32_bf16 v[16:19], v[132:135], v[200:203], v[16:19]
	v_mfma_f32_16x16x32_bf16 v[20:23], v[136:139], v[196:199], v[20:23]
	v_mfma_f32_16x16x32_bf16 v[20:23], v[140:143], v[200:203], v[20:23]
	v_mfma_f32_16x16x32_bf16 v[0:3], v[128:131], v[204:207], v[0:3]
	v_mfma_f32_16x16x32_bf16 v[0:3], v[132:135], v[208:211], v[0:3]
	v_mfma_f32_16x16x32_bf16 v[4:7], v[136:139], v[204:207], v[4:7]
	v_mfma_f32_16x16x32_bf16 v[4:7], v[140:143], v[208:211], v[4:7]
	s_setprio 0
	s_setprio 1
	v_mfma_f32_16x16x32_bf16 v[56:59], v[158:161], v[180:183], v[56:59]
	v_mfma_f32_16x16x32_bf16 v[56:59], v[162:165], v[184:187], v[56:59]
	v_mfma_f32_16x16x32_bf16 v[60:63], v[172:175], v[180:183], v[60:63]
	v_mfma_f32_16x16x32_bf16 v[60:63], v[176:179], v[184:187], v[60:63]
	v_mfma_f32_16x16x32_bf16 v[40:43], v[158:161], v[188:191], v[40:43]
	v_mfma_f32_16x16x32_bf16 v[40:43], v[162:165], v[192:195], v[40:43]
	v_mfma_f32_16x16x32_bf16 v[44:47], v[172:175], v[188:191], v[44:47]
	v_mfma_f32_16x16x32_bf16 v[44:47], v[176:179], v[192:195], v[44:47]
	v_mfma_f32_16x16x32_bf16 v[24:27], v[158:161], v[196:199], v[24:27]
	v_mfma_f32_16x16x32_bf16 v[24:27], v[162:165], v[200:203], v[24:27]
	v_mfma_f32_16x16x32_bf16 v[28:31], v[172:175], v[196:199], v[28:31]
	v_mfma_f32_16x16x32_bf16 v[28:31], v[176:179], v[200:203], v[28:31]
	v_mfma_f32_16x16x32_bf16 v[8:11], v[158:161], v[204:207], v[8:11]
	v_mfma_f32_16x16x32_bf16 v[8:11], v[162:165], v[208:211], v[8:11]
	v_mfma_f32_16x16x32_bf16 v[12:15], v[172:175], v[204:207], v[12:15]
	v_mfma_f32_16x16x32_bf16 v[12:15], v[176:179], v[208:211], v[12:15]
	s_barrier
	s_setprio 0
	s_add_i32 s36, s36, 2
	s_add_u32 s34, s34, 0x100
	s_addc_u32 s35, s35, 0
	s_add_u32 s22, s22, 0x100
	s_addc_u32 s23, s23, 0
	s_cmp_gt_u32 s36, 5
	s_cbranch_scc0 .LBB0_1693
	v_readlane_b32 s22, v254, 27
	v_readlane_b32 s23, v254, 28
	s_and_b64 vcc, exec, s[22:23]
	s_cbranch_vccz .LBB0_1696
	s_barrier

.LBB0_2020:
	ds_read_b128 v[128:131], v244
	ds_read_b128 v[132:135], v244 offset:1024
	ds_read_b128 v[136:139], v244 offset:2048
	ds_read_b128 v[140:143], v244 offset:3072
	ds_read_b128 v[144:147], v245
	ds_read_b128 v[148:151], v245 offset:1024
	ds_read_b128 v[152:155], v245 offset:2048
	ds_read_b128 v[156:159], v245 offset:3072
	s_add_i32 s71, s46, 2
	s_add_u32 s47, s44, 0xfff00080
	s_addc_u32 s48, s45, -1
	s_cmp_eq_u32 s68, s46
	s_cselect_b32 s46, s43, s69
	s_cselect_b32 s49, s5, s48
	s_cselect_b32 s48, s23, s47
	s_cselect_b32 s47, s21, s70
	v_lshl_add_u64 v[192:193], s[44:45], 0, v[218:219]
	s_add_i32 m0, s94, 0xc000
	ds_read_b128 v[160:163], v246
	ds_read_b128 v[164:167], v246 offset:1024
	ds_read_b128 v[168:171], v246 offset:2048
	ds_read_b128 v[172:175], v246 offset:3072
	ds_read_b128 v[176:179], v246 offset:4096
	ds_read_b128 v[180:183], v246 offset:5120
	ds_read_b128 v[184:187], v246 offset:6144
	ds_read_b128 v[188:191], v246 offset:7168
	global_load_lds_dwordx4 v[192:193], off
	v_lshl_add_u64 v[192:193], s[44:45], 0, v[220:221]
	s_add_i32 m0, s94, 0xe000
	s_nop 0
	global_load_lds_dwordx4 v[192:193], off
	s_waitcnt vmcnt(8)
	s_waitcnt lgkmcnt(0)
	s_setprio 1
	s_barrier
	v_mfma_f32_16x16x32_bf16 v[112:115], v[128:131], v[160:163], v[112:115]
	v_mfma_f32_16x16x32_bf16 v[112:115], v[132:135], v[164:167], v[112:115]
	v_mfma_f32_16x16x32_bf16 v[116:119], v[136:139], v[160:163], v[116:119]
	v_mfma_f32_16x16x32_bf16 v[116:119], v[140:143], v[164:167], v[116:119]
	v_mfma_f32_16x16x32_bf16 v[100:103], v[128:131], v[168:171], v[100:103]
	v_mfma_f32_16x16x32_bf16 v[100:103], v[132:135], v[172:175], v[100:103]
	v_mfma_f32_16x16x32_bf16 v[96:99], v[136:139], v[168:171], v[96:99]
	v_mfma_f32_16x16x32_bf16 v[96:99], v[140:143], v[172:175], v[96:99]
	v_mfma_f32_16x16x32_bf16 v[84:87], v[128:131], v[176:179], v[84:87]
	v_mfma_f32_16x16x32_bf16 v[84:87], v[132:135], v[180:183], v[84:87]
	v_mfma_f32_16x16x32_bf16 v[80:83], v[136:139], v[176:179], v[80:83]
	v_mfma_f32_16x16x32_bf16 v[80:83], v[140:143], v[180:183], v[80:83]
	v_mfma_f32_16x16x32_bf16 v[52:55], v[128:131], v[184:187], v[52:55]
	v_mfma_f32_16x16x32_bf16 v[52:55], v[132:135], v[188:191], v[52:55]
	v_mfma_f32_16x16x32_bf16 v[48:51], v[136:139], v[184:187], v[48:51]
	v_mfma_f32_16x16x32_bf16 v[48:51], v[140:143], v[188:191], v[48:51]
	s_setprio 0
	s_setprio 1
	v_mfma_f32_16x16x32_bf16 v[124:127], v[144:147], v[160:163], v[124:127]
	v_mfma_f32_16x16x32_bf16 v[124:127], v[148:151], v[164:167], v[124:127]
	v_mfma_f32_16x16x32_bf16 v[120:123], v[152:155], v[160:163], v[120:123]
	v_mfma_f32_16x16x32_bf16 v[120:123], v[156:159], v[164:167], v[120:123]
	v_mfma_f32_16x16x32_bf16 v[108:111], v[144:147], v[168:171], v[108:111]
	v_mfma_f32_16x16x32_bf16 v[108:111], v[148:151], v[172:175], v[108:111]
	v_mfma_f32_16x16x32_bf16 v[104:107], v[152:155], v[168:171], v[104:107]
	v_mfma_f32_16x16x32_bf16 v[104:107], v[156:159], v[172:175], v[104:107]
	v_mfma_f32_16x16x32_bf16 v[92:95], v[144:147], v[176:179], v[92:95]
	v_mfma_f32_16x16x32_bf16 v[92:95], v[148:151], v[180:183], v[92:95]
	v_mfma_f32_16x16x32_bf16 v[88:91], v[152:155], v[176:179], v[88:91]
	v_mfma_f32_16x16x32_bf16 v[88:91], v[156:159], v[180:183], v[88:91]
	v_mfma_f32_16x16x32_bf16 v[68:71], v[144:147], v[184:187], v[68:71]
	v_mfma_f32_16x16x32_bf16 v[68:71], v[148:151], v[188:191], v[68:71]
	v_mfma_f32_16x16x32_bf16 v[64:67], v[152:155], v[184:187], v[64:67]
	v_mfma_f32_16x16x32_bf16 v[64:67], v[156:159], v[188:191], v[64:67]
	s_barrier
	s_setprio 0
	s_add_i32 s76, s60, s97
	v_lshl_add_u64 v[192:193], s[46:47], 0, v[210:211]
	s_mov_b32 m0, s76
	ds_read_b128 v[160:163], v246 offset:16384
	ds_read_b128 v[164:167], v246 offset:17408
	ds_read_b128 v[168:171], v246 offset:18432
	ds_read_b128 v[172:175], v246 offset:19456
	ds_read_b128 v[176:179], v246 offset:20480
	ds_read_b128 v[180:183], v246 offset:21504
	ds_read_b128 v[184:187], v246 offset:22528
	ds_read_b128 v[188:191], v246 offset:23552
	global_load_lds_dwordx4 v[192:193], off
	s_add_i32 m0, s76, 0x2000
	s_add_u32 s76, s46, 0x100000
	v_lshl_add_u64 v[194:195], s[46:47], 0, v[214:215]
	s_addc_u32 s77, s47, 0
	s_add_i32 s78, s61, s97
	global_load_lds_dwordx4 v[194:195], off
	v_lshl_add_u64 v[196:197], s[76:77], 0, v[210:211]
	s_mov_b32 m0, s78
	v_lshl_add_u64 v[198:199], s[48:49], 0, v[212:213]
	global_load_lds_dwordx4 v[196:197], off
	v_lshl_add_u64 v[196:197], s[76:77], 0, v[214:215]
	s_add_i32 m0, s78, 0x2000
	s_nop 0
	global_load_lds_dwordx4 v[196:197], off
	v_lshl_add_u64 v[196:197], s[48:49], 0, v[208:209]
	s_mov_b32 m0, s94
	s_nop 0
	global_load_lds_dwordx4 v[196:197], off
	s_mov_b32 m0, s2
	s_nop 0
	global_load_lds_dwordx4 v[198:199], off
	s_waitcnt vmcnt(8)
	s_waitcnt lgkmcnt(0)
	s_setprio 1
	s_barrier
	v_mfma_f32_16x16x32_bf16 v[60:63], v[128:131], v[160:163], v[60:63]
	v_mfma_f32_16x16x32_bf16 v[60:63], v[132:135], v[164:167], v[60:63]
	v_mfma_f32_16x16x32_bf16 v[56:59], v[136:139], v[160:163], v[56:59]
	v_mfma_f32_16x16x32_bf16 v[56:59], v[140:143], v[164:167], v[56:59]
	v_mfma_f32_16x16x32_bf16 v[36:39], v[128:131], v[168:171], v[36:39]
	v_mfma_f32_16x16x32_bf16 v[36:39], v[132:135], v[172:175], v[36:39]
	v_mfma_f32_16x16x32_bf16 v[32:35], v[136:139], v[168:171], v[32:35]
	v_mfma_f32_16x16x32_bf16 v[32:35], v[140:143], v[172:175], v[32:35]
	v_mfma_f32_16x16x32_bf16 v[20:23], v[128:131], v[176:179], v[20:23]
	v_mfma_f32_16x16x32_bf16 v[20:23], v[132:135], v[180:183], v[20:23]
	v_mfma_f32_16x16x32_bf16 v[16:19], v[136:139], v[176:179], v[16:19]
	v_mfma_f32_16x16x32_bf16 v[16:19], v[140:143], v[180:183], v[16:19]
	v_mfma_f32_16x16x32_bf16 v[4:7], v[128:131], v[184:187], v[4:7]
	v_mfma_f32_16x16x32_bf16 v[4:7], v[132:135], v[188:191], v[4:7]
	v_mfma_f32_16x16x32_bf16 v[0:3], v[136:139], v[184:187], v[0:3]
	v_mfma_f32_16x16x32_bf16 v[0:3], v[140:143], v[188:191], v[0:3]
	s_setprio 0
	s_setprio 1
	v_mfma_f32_16x16x32_bf16 v[76:79], v[144:147], v[160:163], v[76:79]
	v_mfma_f32_16x16x32_bf16 v[76:79], v[148:151], v[164:167], v[76:79]
	v_mfma_f32_16x16x32_bf16 v[72:75], v[152:155], v[160:163], v[72:75]
	v_mfma_f32_16x16x32_bf16 v[72:75], v[156:159], v[164:167], v[72:75]
	v_mfma_f32_16x16x32_bf16 v[44:47], v[144:147], v[168:171], v[44:47]
	v_mfma_f32_16x16x32_bf16 v[44:47], v[148:151], v[172:175], v[44:47]
	v_mfma_f32_16x16x32_bf16 v[40:43], v[152:155], v[168:171], v[40:43]
	v_mfma_f32_16x16x32_bf16 v[40:43], v[156:159], v[172:175], v[40:43]
	v_mfma_f32_16x16x32_bf16 v[28:31], v[144:147], v[176:179], v[28:31]
	v_mfma_f32_16x16x32_bf16 v[28:31], v[148:151], v[180:183], v[28:31]
	v_mfma_f32_16x16x32_bf16 v[24:27], v[152:155], v[176:179], v[24:27]
	v_mfma_f32_16x16x32_bf16 v[24:27], v[156:159], v[180:183], v[24:27]
	v_mfma_f32_16x16x32_bf16 v[12:15], v[144:147], v[184:187], v[12:15]
	v_mfma_f32_16x16x32_bf16 v[12:15], v[148:151], v[188:191], v[12:15]
	v_mfma_f32_16x16x32_bf16 v[8:11], v[152:155], v[184:187], v[8:11]
	v_mfma_f32_16x16x32_bf16 v[8:11], v[156:159], v[188:191], v[8:11]
	s_barrier
	s_setprio 0
	s_add_i32 s76, 0, 0x18000
	s_add_i32 s77, 0, 0x1c000
	v_add_u32_e32 v140, s76, v243
	v_add_u32_e32 v156, s77, v243
	ds_read_b128 v[128:131], v140
	ds_read_b128 v[132:135], v140 offset:1024
	ds_read_b128 v[136:139], v140 offset:2048
	ds_read_b128 v[140:143], v140 offset:3072
	ds_read_b128 v[144:147], v156
	ds_read_b128 v[148:151], v156 offset:1024
	ds_read_b128 v[152:155], v156 offset:2048
	ds_read_b128 v[156:159], v156 offset:3072
	s_add_u32 s48, s48, 0x100000
	s_addc_u32 s49, s49, 0
	s_mov_b32 m0, s3
	v_lshl_add_u64 v[200:201], s[48:49], 0, v[208:209]
	ds_read_b128 v[160:163], v246 offset:32768
	ds_read_b128 v[164:167], v246 offset:33792
	ds_read_b128 v[168:171], v246 offset:34816
	ds_read_b128 v[172:175], v246 offset:35840
	ds_read_b128 v[176:179], v246 offset:36864
	ds_read_b128 v[180:183], v246 offset:37888
	ds_read_b128 v[184:187], v246 offset:38912
	ds_read_b128 v[188:191], v246 offset:39936
	global_load_lds_dwordx4 v[200:201], off
	v_lshl_add_u64 v[200:201], s[48:49], 0, v[212:213]
	s_mov_b32 m0, s33
	s_nop 0
	global_load_lds_dwordx4 v[200:201], off
	s_waitcnt vmcnt(8)
	s_waitcnt lgkmcnt(0)
	s_setprio 1
	s_barrier
	v_mfma_f32_16x16x32_bf16 v[112:115], v[128:131], v[160:163], v[112:115]
	v_mfma_f32_16x16x32_bf16 v[112:115], v[132:135], v[164:167], v[112:115]
	v_mfma_f32_16x16x32_bf16 v[116:119], v[136:139], v[160:163], v[116:119]
	v_mfma_f32_16x16x32_bf16 v[116:119], v[140:143], v[164:167], v[116:119]
	v_mfma_f32_16x16x32_bf16 v[100:103], v[128:131], v[168:171], v[100:103]
	v_mfma_f32_16x16x32_bf16 v[100:103], v[132:135], v[172:175], v[100:103]
	v_mfma_f32_16x16x32_bf16 v[96:99], v[136:139], v[168:171], v[96:99]
	v_mfma_f32_16x16x32_bf16 v[96:99], v[140:143], v[172:175], v[96:99]
	v_mfma_f32_16x16x32_bf16 v[84:87], v[128:131], v[176:179], v[84:87]
	v_mfma_f32_16x16x32_bf16 v[84:87], v[132:135], v[180:183], v[84:87]
	v_mfma_f32_16x16x32_bf16 v[80:83], v[136:139], v[176:179], v[80:83]
	v_mfma_f32_16x16x32_bf16 v[80:83], v[140:143], v[180:183], v[80:83]
	v_mfma_f32_16x16x32_bf16 v[52:55], v[128:131], v[184:187], v[52:55]
	v_mfma_f32_16x16x32_bf16 v[52:55], v[132:135], v[188:191], v[52:55]
	v_mfma_f32_16x16x32_bf16 v[48:51], v[136:139], v[184:187], v[48:51]
	v_mfma_f32_16x16x32_bf16 v[48:51], v[140:143], v[188:191], v[48:51]
	s_setprio 0
	s_setprio 1
	v_mfma_f32_16x16x32_bf16 v[124:127], v[144:147], v[160:163], v[124:127]
	v_mfma_f32_16x16x32_bf16 v[124:127], v[148:151], v[164:167], v[124:127]
	v_mfma_f32_16x16x32_bf16 v[120:123], v[152:155], v[160:163], v[120:123]
	v_mfma_f32_16x16x32_bf16 v[120:123], v[156:159], v[164:167], v[120:123]
	v_mfma_f32_16x16x32_bf16 v[108:111], v[144:147], v[168:171], v[108:111]
	v_mfma_f32_16x16x32_bf16 v[108:111], v[148:151], v[172:175], v[108:111]
	v_mfma_f32_16x16x32_bf16 v[104:107], v[152:155], v[168:171], v[104:107]
	v_mfma_f32_16x16x32_bf16 v[104:107], v[156:159], v[172:175], v[104:107]
	v_mfma_f32_16x16x32_bf16 v[92:95], v[144:147], v[176:179], v[92:95]
	v_mfma_f32_16x16x32_bf16 v[92:95], v[148:151], v[180:183], v[92:95]
	v_mfma_f32_16x16x32_bf16 v[88:91], v[152:155], v[176:179], v[88:91]
	v_mfma_f32_16x16x32_bf16 v[88:91], v[156:159], v[180:183], v[88:91]
	v_mfma_f32_16x16x32_bf16 v[68:71], v[144:147], v[184:187], v[68:71]
	v_mfma_f32_16x16x32_bf16 v[68:71], v[148:151], v[188:191], v[68:71]
	v_mfma_f32_16x16x32_bf16 v[64:67], v[152:155], v[184:187], v[64:67]
	v_mfma_f32_16x16x32_bf16 v[64:67], v[156:159], v[188:191], v[64:67]
	s_barrier
	s_setprio 0
	s_add_i32 s48, s76, s97
	v_lshl_add_u64 v[192:193], v[192:193], 0, s[16:17]
	s_mov_b32 m0, s48
	ds_read_b128 v[160:163], v246 offset:49152
	ds_read_b128 v[164:167], v246 offset:50176
	ds_read_b128 v[168:171], v246 offset:51200
	ds_read_b128 v[172:175], v246 offset:52224
	ds_read_b128 v[176:179], v246 offset:53248
	ds_read_b128 v[180:183], v246 offset:54272
	ds_read_b128 v[184:187], v246 offset:55296
	ds_read_b128 v[188:191], v246 offset:56320
	global_load_lds_dwordx4 v[192:193], off
	s_add_i32 m0, s48, 0x2000
	s_add_u32 s46, s46, 0x100080
	v_lshl_add_u64 v[192:193], v[194:195], 0, s[16:17]
	s_addc_u32 s47, s47, 0
	s_add_i32 s48, s77, s97
	global_load_lds_dwordx4 v[192:193], off
	v_lshl_add_u64 v[192:193], s[46:47], 0, v[210:211]
	s_mov_b32 m0, s48
	s_nop 0
	global_load_lds_dwordx4 v[192:193], off
	v_lshl_add_u64 v[192:193], s[46:47], 0, v[214:215]
	s_add_i32 m0, s48, 0x2000
	s_nop 0
	global_load_lds_dwordx4 v[192:193], off
	v_lshl_add_u64 v[192:193], v[196:197], 0, s[16:17]
	s_mov_b32 m0, s54
	s_nop 0
	global_load_lds_dwordx4 v[192:193], off
	v_lshl_add_u64 v[192:193], v[198:199], 0, s[16:17]
	s_mov_b32 m0, s55
	s_nop 0
	global_load_lds_dwordx4 v[192:193], off
	s_waitcnt vmcnt(8)
	s_waitcnt lgkmcnt(0)
	s_setprio 1
	s_barrier
	v_mfma_f32_16x16x32_bf16 v[60:63], v[128:131], v[160:163], v[60:63]
	v_mfma_f32_16x16x32_bf16 v[60:63], v[132:135], v[164:167], v[60:63]
	v_mfma_f32_16x16x32_bf16 v[56:59], v[136:139], v[160:163], v[56:59]
	v_mfma_f32_16x16x32_bf16 v[56:59], v[140:143], v[164:167], v[56:59]
	v_mfma_f32_16x16x32_bf16 v[36:39], v[128:131], v[168:171], v[36:39]
	v_mfma_f32_16x16x32_bf16 v[36:39], v[132:135], v[172:175], v[36:39]
	v_mfma_f32_16x16x32_bf16 v[32:35], v[136:139], v[168:171], v[32:35]
	v_mfma_f32_16x16x32_bf16 v[32:35], v[140:143], v[172:175], v[32:35]
	v_mfma_f32_16x16x32_bf16 v[20:23], v[128:131], v[176:179], v[20:23]
	v_mfma_f32_16x16x32_bf16 v[20:23], v[132:135], v[180:183], v[20:23]
	v_mfma_f32_16x16x32_bf16 v[16:19], v[136:139], v[176:179], v[16:19]
	v_mfma_f32_16x16x32_bf16 v[16:19], v[140:143], v[180:183], v[16:19]
	v_mfma_f32_16x16x32_bf16 v[4:7], v[128:131], v[184:187], v[4:7]
	v_mfma_f32_16x16x32_bf16 v[4:7], v[132:135], v[188:191], v[4:7]
	v_mfma_f32_16x16x32_bf16 v[0:3], v[136:139], v[184:187], v[0:3]
	v_mfma_f32_16x16x32_bf16 v[0:3], v[140:143], v[188:191], v[0:3]
	s_setprio 0
	s_setprio 1
	v_mfma_f32_16x16x32_bf16 v[76:79], v[144:147], v[160:163], v[76:79]
	v_mfma_f32_16x16x32_bf16 v[76:79], v[148:151], v[164:167], v[76:79]
	v_mfma_f32_16x16x32_bf16 v[72:75], v[152:155], v[160:163], v[72:75]
	v_mfma_f32_16x16x32_bf16 v[72:75], v[156:159], v[164:167], v[72:75]
	v_mfma_f32_16x16x32_bf16 v[44:47], v[144:147], v[168:171], v[44:47]
	v_mfma_f32_16x16x32_bf16 v[44:47], v[148:151], v[172:175], v[44:47]
	v_mfma_f32_16x16x32_bf16 v[40:43], v[152:155], v[168:171], v[40:43]
	v_mfma_f32_16x16x32_bf16 v[40:43], v[156:159], v[172:175], v[40:43]
	v_mfma_f32_16x16x32_bf16 v[28:31], v[144:147], v[176:179], v[28:31]
	v_mfma_f32_16x16x32_bf16 v[28:31], v[148:151], v[180:183], v[28:31]
	v_mfma_f32_16x16x32_bf16 v[24:27], v[152:155], v[176:179], v[24:27]
	v_mfma_f32_16x16x32_bf16 v[24:27], v[156:159], v[180:183], v[24:27]
	v_mfma_f32_16x16x32_bf16 v[12:15], v[144:147], v[184:187], v[12:15]
	v_mfma_f32_16x16x32_bf16 v[12:15], v[148:151], v[188:191], v[12:15]
	v_mfma_f32_16x16x32_bf16 v[8:11], v[152:155], v[184:187], v[8:11]
	v_mfma_f32_16x16x32_bf16 v[8:11], v[156:159], v[188:191], v[8:11]
	s_barrier
	s_setprio 0
	s_add_u32 s69, s69, 0x100
	s_addc_u32 s70, s70, 0
	s_add_u32 s44, s44, 0x100
	s_addc_u32 s45, s45, 0
	s_cmp_ge_u32 s71, s67
	s_mov_b32 s46, s71
	s_cbranch_scc0 .LBB0_2020
	v_readlane_b32 s44, v254, 27
	v_readlane_b32 s45, v254, 28
	s_and_b64 vcc, exec, s[44:45]
	s_cbranch_vccz .LBB0_2028
	s_barrier
	s_cmp_lt_i32 s14, 0
	s_mov_b64 s[44:45], -1
	s_cbranch_scc1 .LBB0_2029

.LBB0_2289:
	ds_read_b128 v[148:151], v159
	ds_read_b128 v[164:167], v159 offset:1024
	ds_read_b128 v[168:171], v159 offset:2048
	ds_read_b128 v[172:175], v159 offset:3072
	ds_read_b128 v[176:179], v160
	ds_read_b128 v[180:183], v160 offset:1024
	ds_read_b128 v[184:187], v160 offset:2048
	ds_read_b128 v[188:191], v160 offset:3072
	s_add_i32 s87, s46, 2
	s_add_u32 s47, s44, 0xfff00080
	s_addc_u32 s48, s45, -1
	s_cmp_eq_u32 s43, s46
	s_cselect_b32 s46, s25, s85
	s_cselect_b32 s49, s37, s48
	s_cselect_b32 s48, s36, s47
	s_cselect_b32 s47, s5, s86
	v_lshl_add_u64 v[152:153], s[44:45], 0, v[142:143]
	s_add_i32 m0, s94, 0xc000
	ds_read_b128 v[192:195], v161
	ds_read_b128 v[196:199], v161 offset:1024
	ds_read_b128 v[200:203], v161 offset:2048
	ds_read_b128 v[204:207], v161 offset:3072
	ds_read_b128 v[208:211], v161 offset:4096
	ds_read_b128 v[212:215], v161 offset:5120
	ds_read_b128 v[216:219], v161 offset:6144
	ds_read_b128 v[220:223], v161 offset:7168
	global_load_lds_dwordx4 v[152:153], off
	v_lshl_add_u64 v[152:153], s[44:45], 0, v[144:145]
	s_add_i32 m0, s94, 0xe000
	s_nop 0
	global_load_lds_dwordx4 v[152:153], off
	s_waitcnt vmcnt(8)
	s_waitcnt lgkmcnt(0)
	s_setprio 1
	s_barrier
	v_mfma_f32_16x16x32_bf16 v[112:115], v[148:151], v[192:195], v[112:115]
	v_mfma_f32_16x16x32_bf16 v[112:115], v[164:167], v[196:199], v[112:115]
	v_mfma_f32_16x16x32_bf16 v[116:119], v[168:171], v[192:195], v[116:119]
	v_mfma_f32_16x16x32_bf16 v[116:119], v[172:175], v[196:199], v[116:119]
	v_mfma_f32_16x16x32_bf16 v[100:103], v[148:151], v[200:203], v[100:103]
	v_mfma_f32_16x16x32_bf16 v[100:103], v[164:167], v[204:207], v[100:103]
	v_mfma_f32_16x16x32_bf16 v[96:99], v[168:171], v[200:203], v[96:99]
	v_mfma_f32_16x16x32_bf16 v[96:99], v[172:175], v[204:207], v[96:99]
	v_mfma_f32_16x16x32_bf16 v[84:87], v[148:151], v[208:211], v[84:87]
	v_mfma_f32_16x16x32_bf16 v[84:87], v[164:167], v[212:215], v[84:87]
	v_mfma_f32_16x16x32_bf16 v[80:83], v[168:171], v[208:211], v[80:83]
	v_mfma_f32_16x16x32_bf16 v[80:83], v[172:175], v[212:215], v[80:83]
	v_mfma_f32_16x16x32_bf16 v[52:55], v[148:151], v[216:219], v[52:55]
	v_mfma_f32_16x16x32_bf16 v[52:55], v[164:167], v[220:223], v[52:55]
	v_mfma_f32_16x16x32_bf16 v[48:51], v[168:171], v[216:219], v[48:51]
	v_mfma_f32_16x16x32_bf16 v[48:51], v[172:175], v[220:223], v[48:51]
	s_setprio 0
	s_setprio 1
	v_mfma_f32_16x16x32_bf16 v[124:127], v[176:179], v[192:195], v[124:127]
	v_mfma_f32_16x16x32_bf16 v[124:127], v[180:183], v[196:199], v[124:127]
	v_mfma_f32_16x16x32_bf16 v[120:123], v[184:187], v[192:195], v[120:123]
	v_mfma_f32_16x16x32_bf16 v[120:123], v[188:191], v[196:199], v[120:123]
	v_mfma_f32_16x16x32_bf16 v[108:111], v[176:179], v[200:203], v[108:111]
	v_mfma_f32_16x16x32_bf16 v[108:111], v[180:183], v[204:207], v[108:111]
	v_mfma_f32_16x16x32_bf16 v[104:107], v[184:187], v[200:203], v[104:107]
	v_mfma_f32_16x16x32_bf16 v[104:107], v[188:191], v[204:207], v[104:107]
	v_mfma_f32_16x16x32_bf16 v[92:95], v[176:179], v[208:211], v[92:95]
	v_mfma_f32_16x16x32_bf16 v[92:95], v[180:183], v[212:215], v[92:95]
	v_mfma_f32_16x16x32_bf16 v[88:91], v[184:187], v[208:211], v[88:91]
	v_mfma_f32_16x16x32_bf16 v[88:91], v[188:191], v[212:215], v[88:91]
	v_mfma_f32_16x16x32_bf16 v[68:71], v[176:179], v[216:219], v[68:71]
	v_mfma_f32_16x16x32_bf16 v[68:71], v[180:183], v[220:223], v[68:71]
	v_mfma_f32_16x16x32_bf16 v[64:67], v[184:187], v[216:219], v[64:67]
	v_mfma_f32_16x16x32_bf16 v[64:67], v[188:191], v[220:223], v[64:67]
	s_barrier
	s_setprio 0
	s_add_i32 s88, s77, s97
	v_lshl_add_u64 v[152:153], s[46:47], 0, v[132:133]
	s_mov_b32 m0, s88
	ds_read_b128 v[192:195], v161 offset:16384
	ds_read_b128 v[196:199], v161 offset:17408
	ds_read_b128 v[200:203], v161 offset:18432
	ds_read_b128 v[204:207], v161 offset:19456
	ds_read_b128 v[208:211], v161 offset:20480
	ds_read_b128 v[212:215], v161 offset:21504
	ds_read_b128 v[216:219], v161 offset:22528
	ds_read_b128 v[220:223], v161 offset:23552
	global_load_lds_dwordx4 v[152:153], off
	s_add_i32 m0, s88, 0x2000
	s_add_u32 s88, s46, 0x100000
	v_lshl_add_u64 v[224:225], s[46:47], 0, v[136:137]
	s_addc_u32 s89, s47, 0
	s_add_i32 s90, s78, s97
	global_load_lds_dwordx4 v[224:225], off
	v_lshl_add_u64 v[226:227], s[88:89], 0, v[132:133]
	s_mov_b32 m0, s90
	v_lshl_add_u64 v[228:229], s[48:49], 0, v[134:135]
	global_load_lds_dwordx4 v[226:227], off
	v_lshl_add_u64 v[226:227], s[88:89], 0, v[136:137]
	s_add_i32 m0, s90, 0x2000
	s_nop 0
	global_load_lds_dwordx4 v[226:227], off
	v_lshl_add_u64 v[226:227], s[48:49], 0, v[130:131]
	s_mov_b32 m0, s94
	s_nop 0
	global_load_lds_dwordx4 v[226:227], off
	s_mov_b32 m0, s52
	s_nop 0
	global_load_lds_dwordx4 v[228:229], off
	s_waitcnt vmcnt(8)
	s_waitcnt lgkmcnt(0)
	s_setprio 1
	s_barrier
	v_mfma_f32_16x16x32_bf16 v[60:63], v[148:151], v[192:195], v[60:63]
	v_mfma_f32_16x16x32_bf16 v[60:63], v[164:167], v[196:199], v[60:63]
	v_mfma_f32_16x16x32_bf16 v[56:59], v[168:171], v[192:195], v[56:59]
	v_mfma_f32_16x16x32_bf16 v[56:59], v[172:175], v[196:199], v[56:59]
	v_mfma_f32_16x16x32_bf16 v[36:39], v[148:151], v[200:203], v[36:39]
	v_mfma_f32_16x16x32_bf16 v[36:39], v[164:167], v[204:207], v[36:39]
	v_mfma_f32_16x16x32_bf16 v[32:35], v[168:171], v[200:203], v[32:35]
	v_mfma_f32_16x16x32_bf16 v[32:35], v[172:175], v[204:207], v[32:35]
	v_mfma_f32_16x16x32_bf16 v[20:23], v[148:151], v[208:211], v[20:23]
	v_mfma_f32_16x16x32_bf16 v[20:23], v[164:167], v[212:215], v[20:23]
	v_mfma_f32_16x16x32_bf16 v[16:19], v[168:171], v[208:211], v[16:19]
	v_mfma_f32_16x16x32_bf16 v[16:19], v[172:175], v[212:215], v[16:19]
	v_mfma_f32_16x16x32_bf16 v[4:7], v[148:151], v[216:219], v[4:7]
	v_mfma_f32_16x16x32_bf16 v[4:7], v[164:167], v[220:223], v[4:7]
	v_mfma_f32_16x16x32_bf16 v[0:3], v[168:171], v[216:219], v[0:3]
	v_mfma_f32_16x16x32_bf16 v[0:3], v[172:175], v[220:223], v[0:3]
	s_setprio 0
	s_setprio 1
	v_mfma_f32_16x16x32_bf16 v[76:79], v[176:179], v[192:195], v[76:79]
	v_mfma_f32_16x16x32_bf16 v[76:79], v[180:183], v[196:199], v[76:79]
	v_mfma_f32_16x16x32_bf16 v[72:75], v[184:187], v[192:195], v[72:75]
	v_mfma_f32_16x16x32_bf16 v[72:75], v[188:191], v[196:199], v[72:75]
	v_mfma_f32_16x16x32_bf16 v[44:47], v[176:179], v[200:203], v[44:47]
	v_mfma_f32_16x16x32_bf16 v[44:47], v[180:183], v[204:207], v[44:47]
	v_mfma_f32_16x16x32_bf16 v[40:43], v[184:187], v[200:203], v[40:43]
	v_mfma_f32_16x16x32_bf16 v[40:43], v[188:191], v[204:207], v[40:43]
	v_mfma_f32_16x16x32_bf16 v[28:31], v[176:179], v[208:211], v[28:31]
	v_mfma_f32_16x16x32_bf16 v[28:31], v[180:183], v[212:215], v[28:31]
	v_mfma_f32_16x16x32_bf16 v[24:27], v[184:187], v[208:211], v[24:27]
	v_mfma_f32_16x16x32_bf16 v[24:27], v[188:191], v[212:215], v[24:27]
	v_mfma_f32_16x16x32_bf16 v[12:15], v[176:179], v[216:219], v[12:15]
	v_mfma_f32_16x16x32_bf16 v[12:15], v[180:183], v[220:223], v[12:15]
	v_mfma_f32_16x16x32_bf16 v[8:11], v[184:187], v[216:219], v[8:11]
	v_mfma_f32_16x16x32_bf16 v[8:11], v[188:191], v[220:223], v[8:11]
	s_barrier
	s_setprio 0
	s_add_i32 s88, 0, 0x18000
	v_add_u32_e32 v163, s88, v157
	s_add_i32 s89, 0, 0x1c000
	ds_read_b128 v[148:151], v163
	ds_read_b128 v[164:167], v163 offset:1024
	ds_read_b128 v[168:171], v163 offset:2048
	ds_read_b128 v[172:175], v163 offset:3072
	v_add_u32_e32 v163, s89, v157
	ds_read_b128 v[176:179], v163
	ds_read_b128 v[180:183], v163 offset:1024
	ds_read_b128 v[184:187], v163 offset:2048
	ds_read_b128 v[188:191], v163 offset:3072
	s_add_u32 s48, s48, 0x100000
	s_addc_u32 s49, s49, 0
	s_mov_b32 m0, s53
	v_lshl_add_u64 v[230:231], s[48:49], 0, v[130:131]
	ds_read_b128 v[192:195], v161 offset:32768
	ds_read_b128 v[196:199], v161 offset:33792
	ds_read_b128 v[200:203], v161 offset:34816
	ds_read_b128 v[204:207], v161 offset:35840
	ds_read_b128 v[208:211], v161 offset:36864
	ds_read_b128 v[212:215], v161 offset:37888
	ds_read_b128 v[216:219], v161 offset:38912
	ds_read_b128 v[220:223], v161 offset:39936
	global_load_lds_dwordx4 v[230:231], off
	v_lshl_add_u64 v[230:231], s[48:49], 0, v[134:135]
	s_mov_b32 m0, s54
	s_nop 0
	global_load_lds_dwordx4 v[230:231], off
	s_waitcnt vmcnt(8)
	s_waitcnt lgkmcnt(0)
	s_setprio 1
	s_barrier
	v_mfma_f32_16x16x32_bf16 v[112:115], v[148:151], v[192:195], v[112:115]
	v_mfma_f32_16x16x32_bf16 v[112:115], v[164:167], v[196:199], v[112:115]
	v_mfma_f32_16x16x32_bf16 v[116:119], v[168:171], v[192:195], v[116:119]
	v_mfma_f32_16x16x32_bf16 v[116:119], v[172:175], v[196:199], v[116:119]
	v_mfma_f32_16x16x32_bf16 v[100:103], v[148:151], v[200:203], v[100:103]
	v_mfma_f32_16x16x32_bf16 v[100:103], v[164:167], v[204:207], v[100:103]
	v_mfma_f32_16x16x32_bf16 v[96:99], v[168:171], v[200:203], v[96:99]
	v_mfma_f32_16x16x32_bf16 v[96:99], v[172:175], v[204:207], v[96:99]
	v_mfma_f32_16x16x32_bf16 v[84:87], v[148:151], v[208:211], v[84:87]
	v_mfma_f32_16x16x32_bf16 v[84:87], v[164:167], v[212:215], v[84:87]
	v_mfma_f32_16x16x32_bf16 v[80:83], v[168:171], v[208:211], v[80:83]
	v_mfma_f32_16x16x32_bf16 v[80:83], v[172:175], v[212:215], v[80:83]
	v_mfma_f32_16x16x32_bf16 v[52:55], v[148:151], v[216:219], v[52:55]
	v_mfma_f32_16x16x32_bf16 v[52:55], v[164:167], v[220:223], v[52:55]
	v_mfma_f32_16x16x32_bf16 v[48:51], v[168:171], v[216:219], v[48:51]
	v_mfma_f32_16x16x32_bf16 v[48:51], v[172:175], v[220:223], v[48:51]
	s_setprio 0
	s_setprio 1
	v_mfma_f32_16x16x32_bf16 v[124:127], v[176:179], v[192:195], v[124:127]
	v_mfma_f32_16x16x32_bf16 v[124:127], v[180:183], v[196:199], v[124:127]
	v_mfma_f32_16x16x32_bf16 v[120:123], v[184:187], v[192:195], v[120:123]
	v_mfma_f32_16x16x32_bf16 v[120:123], v[188:191], v[196:199], v[120:123]
	v_mfma_f32_16x16x32_bf16 v[108:111], v[176:179], v[200:203], v[108:111]
	v_mfma_f32_16x16x32_bf16 v[108:111], v[180:183], v[204:207], v[108:111]
	v_mfma_f32_16x16x32_bf16 v[104:107], v[184:187], v[200:203], v[104:107]
	v_mfma_f32_16x16x32_bf16 v[104:107], v[188:191], v[204:207], v[104:107]
	v_mfma_f32_16x16x32_bf16 v[92:95], v[176:179], v[208:211], v[92:95]
	v_mfma_f32_16x16x32_bf16 v[92:95], v[180:183], v[212:215], v[92:95]
	v_mfma_f32_16x16x32_bf16 v[88:91], v[184:187], v[208:211], v[88:91]
	v_mfma_f32_16x16x32_bf16 v[88:91], v[188:191], v[212:215], v[88:91]
	v_mfma_f32_16x16x32_bf16 v[68:71], v[176:179], v[216:219], v[68:71]
	v_mfma_f32_16x16x32_bf16 v[68:71], v[180:183], v[220:223], v[68:71]
	v_mfma_f32_16x16x32_bf16 v[64:67], v[184:187], v[216:219], v[64:67]
	v_mfma_f32_16x16x32_bf16 v[64:67], v[188:191], v[220:223], v[64:67]
	s_barrier
	s_setprio 0
	s_add_i32 s48, s88, s97
	v_lshl_add_u64 v[152:153], v[152:153], 0, s[18:19]
	s_mov_b32 m0, s48
	ds_read_b128 v[192:195], v161 offset:49152
	ds_read_b128 v[196:199], v161 offset:50176
	ds_read_b128 v[200:203], v161 offset:51200
	ds_read_b128 v[204:207], v161 offset:52224
	ds_read_b128 v[208:211], v161 offset:53248
	ds_read_b128 v[212:215], v161 offset:54272
	ds_read_b128 v[216:219], v161 offset:55296
	ds_read_b128 v[220:223], v161 offset:56320
	global_load_lds_dwordx4 v[152:153], off
	s_add_i32 m0, s48, 0x2000
	s_add_u32 s46, s46, 0x100080
	v_lshl_add_u64 v[152:153], v[224:225], 0, s[18:19]
	s_addc_u32 s47, s47, 0
	s_add_i32 s48, s89, s97
	global_load_lds_dwordx4 v[152:153], off
	v_lshl_add_u64 v[152:153], s[46:47], 0, v[132:133]
	s_mov_b32 m0, s48
	s_nop 0
	global_load_lds_dwordx4 v[152:153], off
	v_lshl_add_u64 v[152:153], s[46:47], 0, v[136:137]
	s_add_i32 m0, s48, 0x2000
	s_nop 0
	global_load_lds_dwordx4 v[152:153], off
	v_lshl_add_u64 v[152:153], v[226:227], 0, s[18:19]
	s_mov_b32 m0, s68
	s_nop 0
	global_load_lds_dwordx4 v[152:153], off
	v_lshl_add_u64 v[152:153], v[228:229], 0, s[18:19]
	s_mov_b32 m0, s69
	s_nop 0
	global_load_lds_dwordx4 v[152:153], off
	s_waitcnt vmcnt(8)
	s_waitcnt lgkmcnt(0)
	s_setprio 1
	s_barrier
	v_mfma_f32_16x16x32_bf16 v[60:63], v[148:151], v[192:195], v[60:63]
	v_mfma_f32_16x16x32_bf16 v[60:63], v[164:167], v[196:199], v[60:63]
	v_mfma_f32_16x16x32_bf16 v[56:59], v[168:171], v[192:195], v[56:59]
	v_mfma_f32_16x16x32_bf16 v[56:59], v[172:175], v[196:199], v[56:59]
	v_mfma_f32_16x16x32_bf16 v[36:39], v[148:151], v[200:203], v[36:39]
	v_mfma_f32_16x16x32_bf16 v[36:39], v[164:167], v[204:207], v[36:39]
	v_mfma_f32_16x16x32_bf16 v[32:35], v[168:171], v[200:203], v[32:35]
	v_mfma_f32_16x16x32_bf16 v[32:35], v[172:175], v[204:207], v[32:35]
	v_mfma_f32_16x16x32_bf16 v[20:23], v[148:151], v[208:211], v[20:23]
	v_mfma_f32_16x16x32_bf16 v[20:23], v[164:167], v[212:215], v[20:23]
	v_mfma_f32_16x16x32_bf16 v[16:19], v[168:171], v[208:211], v[16:19]
	v_mfma_f32_16x16x32_bf16 v[16:19], v[172:175], v[212:215], v[16:19]
	v_mfma_f32_16x16x32_bf16 v[4:7], v[148:151], v[216:219], v[4:7]
	v_mfma_f32_16x16x32_bf16 v[4:7], v[164:167], v[220:223], v[4:7]
	v_mfma_f32_16x16x32_bf16 v[0:3], v[168:171], v[216:219], v[0:3]
	v_mfma_f32_16x16x32_bf16 v[0:3], v[172:175], v[220:223], v[0:3]
	s_setprio 0
	s_setprio 1
	v_mfma_f32_16x16x32_bf16 v[76:79], v[176:179], v[192:195], v[76:79]
	v_mfma_f32_16x16x32_bf16 v[76:79], v[180:183], v[196:199], v[76:79]
	v_mfma_f32_16x16x32_bf16 v[72:75], v[184:187], v[192:195], v[72:75]
	v_mfma_f32_16x16x32_bf16 v[72:75], v[188:191], v[196:199], v[72:75]
	v_mfma_f32_16x16x32_bf16 v[44:47], v[176:179], v[200:203], v[44:47]
	v_mfma_f32_16x16x32_bf16 v[44:47], v[180:183], v[204:207], v[44:47]
	v_mfma_f32_16x16x32_bf16 v[40:43], v[184:187], v[200:203], v[40:43]
	v_mfma_f32_16x16x32_bf16 v[40:43], v[188:191], v[204:207], v[40:43]
	v_mfma_f32_16x16x32_bf16 v[28:31], v[176:179], v[208:211], v[28:31]
	v_mfma_f32_16x16x32_bf16 v[28:31], v[180:183], v[212:215], v[28:31]
	v_mfma_f32_16x16x32_bf16 v[24:27], v[184:187], v[208:211], v[24:27]
	v_mfma_f32_16x16x32_bf16 v[24:27], v[188:191], v[212:215], v[24:27]
	v_mfma_f32_16x16x32_bf16 v[12:15], v[176:179], v[216:219], v[12:15]
	v_mfma_f32_16x16x32_bf16 v[12:15], v[180:183], v[220:223], v[12:15]
	v_mfma_f32_16x16x32_bf16 v[8:11], v[184:187], v[216:219], v[8:11]
	v_mfma_f32_16x16x32_bf16 v[8:11], v[188:191], v[220:223], v[8:11]
	s_barrier
	s_setprio 0
	s_add_u32 s85, s85, 0x100
	s_addc_u32 s86, s86, 0
	s_add_u32 s44, s44, 0x100
	s_addc_u32 s45, s45, 0
	s_cmp_ge_u32 s87, s84
	s_mov_b32 s46, s87
	s_cbranch_scc0 .LBB0_2289
	v_readlane_b32 s44, v254, 27
	v_readlane_b32 s45, v254, 28
	s_and_b64 vcc, exec, s[44:45]
	s_cbranch_vccz .LBB0_2297
	s_barrier
	s_cmp_lt_i32 s16, 0
	s_mov_b64 s[44:45], -1
	s_cbranch_scc1 .LBB0_2298

.LBB0_2453:
	ds_read_b128 v[128:131], v228
	ds_read_b128 v[132:135], v228 offset:1024
	ds_read_b128 v[136:139], v228 offset:2048
	ds_read_b128 v[140:143], v228 offset:3072
	ds_read_b128 v[144:147], v229
	ds_read_b128 v[148:151], v229 offset:1024
	ds_read_b128 v[152:155], v229 offset:2048
	ds_read_b128 v[156:159], v229 offset:3072
	s_add_i32 s79, s46, 2
	s_add_u32 s47, s44, 0xffc00080
	s_addc_u32 s48, s45, -1
	s_cmp_eq_u32 s75, s46
	s_cselect_b32 s46, s43, s77
	s_cselect_b32 s49, s35, s48
	s_cselect_b32 s48, s41, s47
	s_cselect_b32 s47, s31, s78
	v_lshl_add_u64 v[208:209], s[44:45], 0, v[202:203]
	s_add_i32 m0, s94, 0xc000
	ds_read_b128 v[160:163], v230
	ds_read_b128 v[164:167], v230 offset:1024
	ds_read_b128 v[168:171], v230 offset:2048
	ds_read_b128 v[172:175], v230 offset:3072
	ds_read_b128 v[176:179], v230 offset:4096
	ds_read_b128 v[180:183], v230 offset:5120
	ds_read_b128 v[184:187], v230 offset:6144
	ds_read_b128 v[188:191], v230 offset:7168
	global_load_lds_dwordx4 v[208:209], off
	v_lshl_add_u64 v[208:209], s[44:45], 0, v[204:205]
	s_add_i32 m0, s94, 0xe000
	s_nop 0
	global_load_lds_dwordx4 v[208:209], off
	s_waitcnt vmcnt(8)
	s_waitcnt lgkmcnt(0)
	s_setprio 1
	s_barrier
	v_mfma_f32_16x16x32_bf16 v[112:115], v[128:131], v[160:163], v[112:115]
	v_mfma_f32_16x16x32_bf16 v[112:115], v[132:135], v[164:167], v[112:115]
	v_mfma_f32_16x16x32_bf16 v[116:119], v[136:139], v[160:163], v[116:119]
	v_mfma_f32_16x16x32_bf16 v[116:119], v[140:143], v[164:167], v[116:119]
	v_mfma_f32_16x16x32_bf16 v[100:103], v[128:131], v[168:171], v[100:103]
	v_mfma_f32_16x16x32_bf16 v[100:103], v[132:135], v[172:175], v[100:103]
	v_mfma_f32_16x16x32_bf16 v[96:99], v[136:139], v[168:171], v[96:99]
	v_mfma_f32_16x16x32_bf16 v[96:99], v[140:143], v[172:175], v[96:99]
	v_mfma_f32_16x16x32_bf16 v[84:87], v[128:131], v[176:179], v[84:87]
	v_mfma_f32_16x16x32_bf16 v[84:87], v[132:135], v[180:183], v[84:87]
	v_mfma_f32_16x16x32_bf16 v[80:83], v[136:139], v[176:179], v[80:83]
	v_mfma_f32_16x16x32_bf16 v[80:83], v[140:143], v[180:183], v[80:83]
	v_mfma_f32_16x16x32_bf16 v[52:55], v[128:131], v[184:187], v[52:55]
	v_mfma_f32_16x16x32_bf16 v[52:55], v[132:135], v[188:191], v[52:55]
	v_mfma_f32_16x16x32_bf16 v[48:51], v[136:139], v[184:187], v[48:51]
	v_mfma_f32_16x16x32_bf16 v[48:51], v[140:143], v[188:191], v[48:51]
	s_setprio 0
	s_setprio 1
	v_mfma_f32_16x16x32_bf16 v[124:127], v[144:147], v[160:163], v[124:127]
	v_mfma_f32_16x16x32_bf16 v[124:127], v[148:151], v[164:167], v[124:127]
	v_mfma_f32_16x16x32_bf16 v[120:123], v[152:155], v[160:163], v[120:123]
	v_mfma_f32_16x16x32_bf16 v[120:123], v[156:159], v[164:167], v[120:123]
	v_mfma_f32_16x16x32_bf16 v[108:111], v[144:147], v[168:171], v[108:111]
	v_mfma_f32_16x16x32_bf16 v[108:111], v[148:151], v[172:175], v[108:111]
	v_mfma_f32_16x16x32_bf16 v[104:107], v[152:155], v[168:171], v[104:107]
	v_mfma_f32_16x16x32_bf16 v[104:107], v[156:159], v[172:175], v[104:107]
	v_mfma_f32_16x16x32_bf16 v[92:95], v[144:147], v[176:179], v[92:95]
	v_mfma_f32_16x16x32_bf16 v[92:95], v[148:151], v[180:183], v[92:95]
	v_mfma_f32_16x16x32_bf16 v[88:91], v[152:155], v[176:179], v[88:91]
	v_mfma_f32_16x16x32_bf16 v[88:91], v[156:159], v[180:183], v[88:91]
	v_mfma_f32_16x16x32_bf16 v[68:71], v[144:147], v[184:187], v[68:71]
	v_mfma_f32_16x16x32_bf16 v[68:71], v[148:151], v[188:191], v[68:71]
	v_mfma_f32_16x16x32_bf16 v[64:67], v[152:155], v[184:187], v[64:67]
	v_mfma_f32_16x16x32_bf16 v[64:67], v[156:159], v[188:191], v[64:67]
	s_barrier
	s_setprio 0
	s_add_i32 s80, s68, s97
	v_lshl_add_u64 v[208:209], s[46:47], 0, v[194:195]
	s_mov_b32 m0, s80
	ds_read_b128 v[160:163], v230 offset:16384
	ds_read_b128 v[164:167], v230 offset:17408
	ds_read_b128 v[168:171], v230 offset:18432
	ds_read_b128 v[172:175], v230 offset:19456
	ds_read_b128 v[176:179], v230 offset:20480
	ds_read_b128 v[180:183], v230 offset:21504
	ds_read_b128 v[184:187], v230 offset:22528
	ds_read_b128 v[188:191], v230 offset:23552
	global_load_lds_dwordx4 v[208:209], off
	s_add_i32 m0, s80, 0x2000
	s_add_u32 s80, s46, 0x400000
	v_lshl_add_u64 v[210:211], s[46:47], 0, v[198:199]
	s_addc_u32 s81, s47, 0
	s_add_i32 s84, s69, s97
	global_load_lds_dwordx4 v[210:211], off
	v_lshl_add_u64 v[212:213], s[80:81], 0, v[194:195]
	s_mov_b32 m0, s84
	v_lshl_add_u64 v[214:215], s[48:49], 0, v[196:197]
	global_load_lds_dwordx4 v[212:213], off
	v_lshl_add_u64 v[212:213], s[80:81], 0, v[198:199]
	s_add_i32 m0, s84, 0x2000
	s_nop 0
	global_load_lds_dwordx4 v[212:213], off
	v_lshl_add_u64 v[212:213], s[48:49], 0, v[192:193]
	s_mov_b32 m0, s94
	s_nop 0
	global_load_lds_dwordx4 v[212:213], off
	s_mov_b32 m0, s51
	s_nop 0
	global_load_lds_dwordx4 v[214:215], off
	s_waitcnt vmcnt(8)
	s_waitcnt lgkmcnt(0)
	s_setprio 1
	s_barrier
	v_mfma_f32_16x16x32_bf16 v[60:63], v[128:131], v[160:163], v[60:63]
	v_mfma_f32_16x16x32_bf16 v[60:63], v[132:135], v[164:167], v[60:63]
	v_mfma_f32_16x16x32_bf16 v[56:59], v[136:139], v[160:163], v[56:59]
	v_mfma_f32_16x16x32_bf16 v[56:59], v[140:143], v[164:167], v[56:59]
	v_mfma_f32_16x16x32_bf16 v[36:39], v[128:131], v[168:171], v[36:39]
	v_mfma_f32_16x16x32_bf16 v[36:39], v[132:135], v[172:175], v[36:39]
	v_mfma_f32_16x16x32_bf16 v[32:35], v[136:139], v[168:171], v[32:35]
	v_mfma_f32_16x16x32_bf16 v[32:35], v[140:143], v[172:175], v[32:35]
	v_mfma_f32_16x16x32_bf16 v[20:23], v[128:131], v[176:179], v[20:23]
	v_mfma_f32_16x16x32_bf16 v[20:23], v[132:135], v[180:183], v[20:23]
	v_mfma_f32_16x16x32_bf16 v[16:19], v[136:139], v[176:179], v[16:19]
	v_mfma_f32_16x16x32_bf16 v[16:19], v[140:143], v[180:183], v[16:19]
	v_mfma_f32_16x16x32_bf16 v[4:7], v[128:131], v[184:187], v[4:7]
	v_mfma_f32_16x16x32_bf16 v[4:7], v[132:135], v[188:191], v[4:7]
	v_mfma_f32_16x16x32_bf16 v[0:3], v[136:139], v[184:187], v[0:3]
	v_mfma_f32_16x16x32_bf16 v[0:3], v[140:143], v[188:191], v[0:3]
	s_setprio 0
	s_setprio 1
	v_mfma_f32_16x16x32_bf16 v[76:79], v[144:147], v[160:163], v[76:79]
	v_mfma_f32_16x16x32_bf16 v[76:79], v[148:151], v[164:167], v[76:79]
	v_mfma_f32_16x16x32_bf16 v[72:75], v[152:155], v[160:163], v[72:75]
	v_mfma_f32_16x16x32_bf16 v[72:75], v[156:159], v[164:167], v[72:75]
	v_mfma_f32_16x16x32_bf16 v[44:47], v[144:147], v[168:171], v[44:47]
	v_mfma_f32_16x16x32_bf16 v[44:47], v[148:151], v[172:175], v[44:47]
	v_mfma_f32_16x16x32_bf16 v[40:43], v[152:155], v[168:171], v[40:43]
	v_mfma_f32_16x16x32_bf16 v[40:43], v[156:159], v[172:175], v[40:43]
	v_mfma_f32_16x16x32_bf16 v[28:31], v[144:147], v[176:179], v[28:31]
	v_mfma_f32_16x16x32_bf16 v[28:31], v[148:151], v[180:183], v[28:31]
	v_mfma_f32_16x16x32_bf16 v[24:27], v[152:155], v[176:179], v[24:27]
	v_mfma_f32_16x16x32_bf16 v[24:27], v[156:159], v[180:183], v[24:27]
	v_mfma_f32_16x16x32_bf16 v[12:15], v[144:147], v[184:187], v[12:15]
	v_mfma_f32_16x16x32_bf16 v[12:15], v[148:151], v[188:191], v[12:15]
	v_mfma_f32_16x16x32_bf16 v[8:11], v[152:155], v[184:187], v[8:11]
	v_mfma_f32_16x16x32_bf16 v[8:11], v[156:159], v[188:191], v[8:11]
	s_barrier
	s_setprio 0
	s_add_i32 s80, 0, 0x18000
	s_add_i32 s81, 0, 0x1c000
	v_add_u32_e32 v140, s80, v226
	v_add_u32_e32 v156, s81, v226
	ds_read_b128 v[128:131], v140
	ds_read_b128 v[132:135], v140 offset:1024
	ds_read_b128 v[136:139], v140 offset:2048
	ds_read_b128 v[140:143], v140 offset:3072
	ds_read_b128 v[144:147], v156
	ds_read_b128 v[148:151], v156 offset:1024
	ds_read_b128 v[152:155], v156 offset:2048
	ds_read_b128 v[156:159], v156 offset:3072
	s_add_u32 s48, s48, 0x400000
	s_addc_u32 s49, s49, 0
	s_mov_b32 m0, s52
	v_lshl_add_u64 v[216:217], s[48:49], 0, v[192:193]
	ds_read_b128 v[160:163], v230 offset:32768
	ds_read_b128 v[164:167], v230 offset:33792
	ds_read_b128 v[168:171], v230 offset:34816
	ds_read_b128 v[172:175], v230 offset:35840
	ds_read_b128 v[176:179], v230 offset:36864
	ds_read_b128 v[180:183], v230 offset:37888
	ds_read_b128 v[184:187], v230 offset:38912
	ds_read_b128 v[188:191], v230 offset:39936
	global_load_lds_dwordx4 v[216:217], off
	v_lshl_add_u64 v[216:217], s[48:49], 0, v[196:197]
	s_mov_b32 m0, s53
	s_nop 0
	global_load_lds_dwordx4 v[216:217], off
	s_waitcnt vmcnt(8)
	s_waitcnt lgkmcnt(0)
	s_setprio 1
	s_barrier
	v_mfma_f32_16x16x32_bf16 v[112:115], v[128:131], v[160:163], v[112:115]
	v_mfma_f32_16x16x32_bf16 v[112:115], v[132:135], v[164:167], v[112:115]
	v_mfma_f32_16x16x32_bf16 v[116:119], v[136:139], v[160:163], v[116:119]
	v_mfma_f32_16x16x32_bf16 v[116:119], v[140:143], v[164:167], v[116:119]
	v_mfma_f32_16x16x32_bf16 v[100:103], v[128:131], v[168:171], v[100:103]
	v_mfma_f32_16x16x32_bf16 v[100:103], v[132:135], v[172:175], v[100:103]
	v_mfma_f32_16x16x32_bf16 v[96:99], v[136:139], v[168:171], v[96:99]
	v_mfma_f32_16x16x32_bf16 v[96:99], v[140:143], v[172:175], v[96:99]
	v_mfma_f32_16x16x32_bf16 v[84:87], v[128:131], v[176:179], v[84:87]
	v_mfma_f32_16x16x32_bf16 v[84:87], v[132:135], v[180:183], v[84:87]
	v_mfma_f32_16x16x32_bf16 v[80:83], v[136:139], v[176:179], v[80:83]
	v_mfma_f32_16x16x32_bf16 v[80:83], v[140:143], v[180:183], v[80:83]
	v_mfma_f32_16x16x32_bf16 v[52:55], v[128:131], v[184:187], v[52:55]
	v_mfma_f32_16x16x32_bf16 v[52:55], v[132:135], v[188:191], v[52:55]
	v_mfma_f32_16x16x32_bf16 v[48:51], v[136:139], v[184:187], v[48:51]
	v_mfma_f32_16x16x32_bf16 v[48:51], v[140:143], v[188:191], v[48:51]
	s_setprio 0
	s_setprio 1
	v_mfma_f32_16x16x32_bf16 v[124:127], v[144:147], v[160:163], v[124:127]
	v_mfma_f32_16x16x32_bf16 v[124:127], v[148:151], v[164:167], v[124:127]
	v_mfma_f32_16x16x32_bf16 v[120:123], v[152:155], v[160:163], v[120:123]
	v_mfma_f32_16x16x32_bf16 v[120:123], v[156:159], v[164:167], v[120:123]
	v_mfma_f32_16x16x32_bf16 v[108:111], v[144:147], v[168:171], v[108:111]
	v_mfma_f32_16x16x32_bf16 v[108:111], v[148:151], v[172:175], v[108:111]
	v_mfma_f32_16x16x32_bf16 v[104:107], v[152:155], v[168:171], v[104:107]
	v_mfma_f32_16x16x32_bf16 v[104:107], v[156:159], v[172:175], v[104:107]
	v_mfma_f32_16x16x32_bf16 v[92:95], v[144:147], v[176:179], v[92:95]
	v_mfma_f32_16x16x32_bf16 v[92:95], v[148:151], v[180:183], v[92:95]
	v_mfma_f32_16x16x32_bf16 v[88:91], v[152:155], v[176:179], v[88:91]
	v_mfma_f32_16x16x32_bf16 v[88:91], v[156:159], v[180:183], v[88:91]
	v_mfma_f32_16x16x32_bf16 v[68:71], v[144:147], v[184:187], v[68:71]
	v_mfma_f32_16x16x32_bf16 v[68:71], v[148:151], v[188:191], v[68:71]
	v_mfma_f32_16x16x32_bf16 v[64:67], v[152:155], v[184:187], v[64:67]
	v_mfma_f32_16x16x32_bf16 v[64:67], v[156:159], v[188:191], v[64:67]
	s_barrier
	s_setprio 0
	s_add_i32 s48, s80, s97
	v_lshl_add_u64 v[208:209], v[208:209], 0, s[12:13]
	s_mov_b32 m0, s48
	ds_read_b128 v[160:163], v230 offset:49152
	ds_read_b128 v[164:167], v230 offset:50176
	ds_read_b128 v[168:171], v230 offset:51200
	ds_read_b128 v[172:175], v230 offset:52224
	ds_read_b128 v[176:179], v230 offset:53248
	ds_read_b128 v[180:183], v230 offset:54272
	ds_read_b128 v[184:187], v230 offset:55296
	ds_read_b128 v[188:191], v230 offset:56320
	global_load_lds_dwordx4 v[208:209], off
	s_add_i32 m0, s48, 0x2000
	s_add_u32 s46, s46, 0x400080
	v_lshl_add_u64 v[208:209], v[210:211], 0, s[12:13]
	s_addc_u32 s47, s47, 0
	s_add_i32 s48, s81, s97
	global_load_lds_dwordx4 v[208:209], off
	v_lshl_add_u64 v[208:209], s[46:47], 0, v[194:195]
	s_mov_b32 m0, s48
	s_nop 0
	global_load_lds_dwordx4 v[208:209], off
	v_lshl_add_u64 v[208:209], s[46:47], 0, v[198:199]
	s_add_i32 m0, s48, 0x2000
	s_nop 0
	global_load_lds_dwordx4 v[208:209], off
	v_lshl_add_u64 v[208:209], v[212:213], 0, s[12:13]
	s_mov_b32 m0, s54
	s_nop 0
	global_load_lds_dwordx4 v[208:209], off
	v_lshl_add_u64 v[208:209], v[214:215], 0, s[12:13]
	s_mov_b32 m0, s55
	s_nop 0
	global_load_lds_dwordx4 v[208:209], off
	s_waitcnt vmcnt(8)
	s_waitcnt lgkmcnt(0)
	s_setprio 1
	s_barrier
	v_mfma_f32_16x16x32_bf16 v[60:63], v[128:131], v[160:163], v[60:63]
	v_mfma_f32_16x16x32_bf16 v[60:63], v[132:135], v[164:167], v[60:63]
	v_mfma_f32_16x16x32_bf16 v[56:59], v[136:139], v[160:163], v[56:59]
	v_mfma_f32_16x16x32_bf16 v[56:59], v[140:143], v[164:167], v[56:59]
	v_mfma_f32_16x16x32_bf16 v[36:39], v[128:131], v[168:171], v[36:39]
	v_mfma_f32_16x16x32_bf16 v[36:39], v[132:135], v[172:175], v[36:39]
	v_mfma_f32_16x16x32_bf16 v[32:35], v[136:139], v[168:171], v[32:35]
	v_mfma_f32_16x16x32_bf16 v[32:35], v[140:143], v[172:175], v[32:35]
	v_mfma_f32_16x16x32_bf16 v[20:23], v[128:131], v[176:179], v[20:23]
	v_mfma_f32_16x16x32_bf16 v[20:23], v[132:135], v[180:183], v[20:23]
	v_mfma_f32_16x16x32_bf16 v[16:19], v[136:139], v[176:179], v[16:19]
	v_mfma_f32_16x16x32_bf16 v[16:19], v[140:143], v[180:183], v[16:19]
	v_mfma_f32_16x16x32_bf16 v[4:7], v[128:131], v[184:187], v[4:7]
	v_mfma_f32_16x16x32_bf16 v[4:7], v[132:135], v[188:191], v[4:7]
	v_mfma_f32_16x16x32_bf16 v[0:3], v[136:139], v[184:187], v[0:3]
	v_mfma_f32_16x16x32_bf16 v[0:3], v[140:143], v[188:191], v[0:3]
	s_setprio 0
	s_setprio 1
	v_mfma_f32_16x16x32_bf16 v[76:79], v[144:147], v[160:163], v[76:79]
	v_mfma_f32_16x16x32_bf16 v[76:79], v[148:151], v[164:167], v[76:79]
	v_mfma_f32_16x16x32_bf16 v[72:75], v[152:155], v[160:163], v[72:75]
	v_mfma_f32_16x16x32_bf16 v[72:75], v[156:159], v[164:167], v[72:75]
	v_mfma_f32_16x16x32_bf16 v[44:47], v[144:147], v[168:171], v[44:47]
	v_mfma_f32_16x16x32_bf16 v[44:47], v[148:151], v[172:175], v[44:47]
	v_mfma_f32_16x16x32_bf16 v[40:43], v[152:155], v[168:171], v[40:43]
	v_mfma_f32_16x16x32_bf16 v[40:43], v[156:159], v[172:175], v[40:43]
	v_mfma_f32_16x16x32_bf16 v[28:31], v[144:147], v[176:179], v[28:31]
	v_mfma_f32_16x16x32_bf16 v[28:31], v[148:151], v[180:183], v[28:31]
	v_mfma_f32_16x16x32_bf16 v[24:27], v[152:155], v[176:179], v[24:27]
	v_mfma_f32_16x16x32_bf16 v[24:27], v[156:159], v[180:183], v[24:27]
	v_mfma_f32_16x16x32_bf16 v[12:15], v[144:147], v[184:187], v[12:15]
	v_mfma_f32_16x16x32_bf16 v[12:15], v[148:151], v[188:191], v[12:15]
	v_mfma_f32_16x16x32_bf16 v[8:11], v[152:155], v[184:187], v[8:11]
	v_mfma_f32_16x16x32_bf16 v[8:11], v[156:159], v[188:191], v[8:11]
	s_barrier
	s_setprio 0
	s_add_u32 s77, s77, 0x100
	s_addc_u32 s78, s78, 0
	s_add_u32 s44, s44, 0x100
	s_addc_u32 s45, s45, 0
	s_cmp_ge_u32 s79, s76
	s_mov_b32 s46, s79
	s_cbranch_scc0 .LBB0_2453
	v_readlane_b32 s44, v254, 27
	v_readlane_b32 s45, v254, 28
	s_and_b64 vcc, exec, s[44:45]
	s_cbranch_vccz .LBB0_2461
	s_barrier
	s_cmp_lt_i32 s10, 0
	s_mov_b64 s[44:45], -1
	s_cbranch_scc1 .LBB0_2462
